# v55: P6 first-pass epilogues E1/E2 (sigmoid gates) rewritten by hand incl. tail-row-tile exits (v50 base)
# baseline (speedup 1.0000x reference)
.LBB0_3328:
	s_waitcnt vmcnt(0)
	s_cmpk_lt_i32 s8, 0x4000
	s_cbranch_scc1 .Lp6x_e2_f
	v_readfirstlane_b32 s64, v208
	s_bitcmp1_b32 s64, 8
	s_cbranch_scc1 .Lp6x_e2_e
.Lp6x_e2_f:
	v_lshrrev_b32_e32 v197, 3, v208
	v_and_b32_e32 v197, 4, v197
	v_lshrrev_b32_e32 v195, 1, v208
	v_and_b32_e32 v195, 0x80, v195
	v_or_b32_e32 v195, v195, v197
	v_lshl_add_u32 v194, v195, 2, s33
	ds_read_b128 v[144:147], v194
	ds_read_b128 v[148:151], v194 offset:32
	ds_read_b128 v[152:155], v194 offset:64
	ds_read_b128 v[156:159], v194 offset:96
	ds_read_b128 v[160:163], v194 offset:128
	ds_read_b128 v[164:167], v194 offset:160
	ds_read_b128 v[168:171], v194 offset:192
	ds_read_b128 v[172:175], v194 offset:224
	v_and_b32_e32 v196, 0xdf, v208
	v_or_b32_e32 v196, s10, v196
	v_add_u32_e32 v197, s8, v195
	v_lshlrev_b32_e32 v197, 11, v197
	v_lshl_add_u32 v192, v196, 1, v197
	s_waitcnt lgkmcnt(7)
	v_mul_f32_e32 v176, v128, v144
	v_mul_f32_e32 v177, v129, v145
	v_mul_f32_e32 v178, v130, v146
	v_mul_f32_e32 v179, v131, v147
	v_mul_f32_e32 v180, v112, v144
	v_mul_f32_e32 v181, v113, v145
	v_mul_f32_e32 v182, v114, v146
	v_mul_f32_e32 v183, v115, v147
	ds_read_b128 v[144:147], v194 offset:256
	v_mul_f32_e32 v176, 0xbfb8aa3b, v176
	v_mul_f32_e32 v177, 0xbfb8aa3b, v177
	v_mul_f32_e32 v178, 0xbfb8aa3b, v178
	v_mul_f32_e32 v179, 0xbfb8aa3b, v179
	v_mul_f32_e32 v180, 0xbfb8aa3b, v180
	v_mul_f32_e32 v181, 0xbfb8aa3b, v181
	v_mul_f32_e32 v182, 0xbfb8aa3b, v182
	v_mul_f32_e32 v183, 0xbfb8aa3b, v183
	v_exp_f32_e32 v176, v176
	v_exp_f32_e32 v177, v177
	v_exp_f32_e32 v178, v178
	v_exp_f32_e32 v179, v179
	v_exp_f32_e32 v180, v180
	v_exp_f32_e32 v181, v181
	v_exp_f32_e32 v182, v182
	v_exp_f32_e32 v183, v183
	v_add_f32_e32 v176, 1.0, v176
	v_add_f32_e32 v177, 1.0, v177
	v_add_f32_e32 v178, 1.0, v178
	v_add_f32_e32 v179, 1.0, v179
	v_add_f32_e32 v180, 1.0, v180
	v_add_f32_e32 v181, 1.0, v181
	v_add_f32_e32 v182, 1.0, v182
	v_add_f32_e32 v183, 1.0, v183
	v_rcp_f32_e32 v176, v176
	v_rcp_f32_e32 v177, v177
	v_rcp_f32_e32 v178, v178
	v_rcp_f32_e32 v179, v179
	v_rcp_f32_e32 v180, v180
	v_rcp_f32_e32 v181, v181
	v_rcp_f32_e32 v182, v182
	v_rcp_f32_e32 v183, v183
	v_max_f32_e32 v176, 0x358637bd, v176
	v_max_f32_e32 v177, 0x358637bd, v177
	v_max_f32_e32 v178, 0x358637bd, v178
	v_max_f32_e32 v179, 0x358637bd, v179
	v_max_f32_e32 v180, 0x358637bd, v180
	v_max_f32_e32 v181, 0x358637bd, v181
	v_max_f32_e32 v182, 0x358637bd, v182
	v_max_f32_e32 v183, 0x358637bd, v183
	v_cvt_pk_bf16_f32 v184, v176, v177
	v_cvt_pk_bf16_f32 v185, v178, v179
	v_cvt_pk_bf16_f32 v186, v180, v181
	v_cvt_pk_bf16_f32 v187, v182, v183
	global_store_short v192, v184, s[62:63]
	global_store_short v192, v186, s[62:63] offset:64
	v_add_u32_e32 v192, 0x800, v192
	global_store_short_d16_hi v192, v184, s[62:63]
	global_store_short_d16_hi v192, v186, s[62:63] offset:64
	v_add_u32_e32 v192, 0x800, v192
	global_store_short v192, v185, s[62:63]
	global_store_short v192, v187, s[62:63] offset:64
	v_add_u32_e32 v192, 0x800, v192
	global_store_short_d16_hi v192, v185, s[62:63]
	global_store_short_d16_hi v192, v187, s[62:63] offset:64
	v_add_u32_e32 v192, 0x2800, v192
	s_waitcnt lgkmcnt(7)
	v_mul_f32_e32 v176, v132, v148
	v_mul_f32_e32 v177, v133, v149
	v_mul_f32_e32 v178, v134, v150
	v_mul_f32_e32 v179, v135, v151
	v_mul_f32_e32 v180, v116, v148
	v_mul_f32_e32 v181, v117, v149
	v_mul_f32_e32 v182, v118, v150
	v_mul_f32_e32 v183, v119, v151
	ds_read_b128 v[148:151], v194 offset:288
	v_mul_f32_e32 v176, 0xbfb8aa3b, v176
	v_mul_f32_e32 v177, 0xbfb8aa3b, v177
	v_mul_f32_e32 v178, 0xbfb8aa3b, v178
	v_mul_f32_e32 v179, 0xbfb8aa3b, v179
	v_mul_f32_e32 v180, 0xbfb8aa3b, v180
	v_mul_f32_e32 v181, 0xbfb8aa3b, v181
	v_mul_f32_e32 v182, 0xbfb8aa3b, v182
	v_mul_f32_e32 v183, 0xbfb8aa3b, v183
	v_exp_f32_e32 v176, v176
	v_exp_f32_e32 v177, v177
	v_exp_f32_e32 v178, v178
	v_exp_f32_e32 v179, v179
	v_exp_f32_e32 v180, v180
	v_exp_f32_e32 v181, v181
	v_exp_f32_e32 v182, v182
	v_exp_f32_e32 v183, v183
	v_add_f32_e32 v176, 1.0, v176
	v_add_f32_e32 v177, 1.0, v177
	v_add_f32_e32 v178, 1.0, v178
	v_add_f32_e32 v179, 1.0, v179
	v_add_f32_e32 v180, 1.0, v180
	v_add_f32_e32 v181, 1.0, v181
	v_add_f32_e32 v182, 1.0, v182
	v_add_f32_e32 v183, 1.0, v183
	v_rcp_f32_e32 v176, v176
	v_rcp_f32_e32 v177, v177
	v_rcp_f32_e32 v178, v178
	v_rcp_f32_e32 v179, v179
	v_rcp_f32_e32 v180, v180
	v_rcp_f32_e32 v181, v181
	v_rcp_f32_e32 v182, v182
	v_rcp_f32_e32 v183, v183
	v_max_f32_e32 v176, 0x358637bd, v176
	v_max_f32_e32 v177, 0x358637bd, v177
	v_max_f32_e32 v178, 0x358637bd, v178
	v_max_f32_e32 v179, 0x358637bd, v179
	v_max_f32_e32 v180, 0x358637bd, v180
	v_max_f32_e32 v181, 0x358637bd, v181
	v_max_f32_e32 v182, 0x358637bd, v182
	v_max_f32_e32 v183, 0x358637bd, v183
	v_cvt_pk_bf16_f32 v188, v176, v177
	v_cvt_pk_bf16_f32 v189, v178, v179
	v_cvt_pk_bf16_f32 v190, v180, v181
	v_cvt_pk_bf16_f32 v191, v182, v183
	global_store_short v192, v188, s[62:63]
	global_store_short v192, v190, s[62:63] offset:64
	v_add_u32_e32 v192, 0x800, v192
	global_store_short_d16_hi v192, v188, s[62:63]
	global_store_short_d16_hi v192, v190, s[62:63] offset:64
	v_add_u32_e32 v192, 0x800, v192
	global_store_short v192, v189, s[62:63]
	global_store_short v192, v191, s[62:63] offset:64
	v_add_u32_e32 v192, 0x800, v192
	global_store_short_d16_hi v192, v189, s[62:63]
	global_store_short_d16_hi v192, v191, s[62:63] offset:64
	v_add_u32_e32 v192, 0x2800, v192
	s_waitcnt lgkmcnt(7)
	v_mul_f32_e32 v176, v136, v152
	v_mul_f32_e32 v177, v137, v153
	v_mul_f32_e32 v178, v138, v154
	v_mul_f32_e32 v179, v139, v155
	v_mul_f32_e32 v180, v120, v152
	v_mul_f32_e32 v181, v121, v153
	v_mul_f32_e32 v182, v122, v154
	v_mul_f32_e32 v183, v123, v155
	ds_read_b128 v[152:155], v194 offset:320
	v_mul_f32_e32 v176, 0xbfb8aa3b, v176
	v_mul_f32_e32 v177, 0xbfb8aa3b, v177
	v_mul_f32_e32 v178, 0xbfb8aa3b, v178
	v_mul_f32_e32 v179, 0xbfb8aa3b, v179
	v_mul_f32_e32 v180, 0xbfb8aa3b, v180
	v_mul_f32_e32 v181, 0xbfb8aa3b, v181
	v_mul_f32_e32 v182, 0xbfb8aa3b, v182
	v_mul_f32_e32 v183, 0xbfb8aa3b, v183
	v_exp_f32_e32 v176, v176
	v_exp_f32_e32 v177, v177
	v_exp_f32_e32 v178, v178
	v_exp_f32_e32 v179, v179
	v_exp_f32_e32 v180, v180
	v_exp_f32_e32 v181, v181
	v_exp_f32_e32 v182, v182
	v_exp_f32_e32 v183, v183
	v_add_f32_e32 v176, 1.0, v176
	v_add_f32_e32 v177, 1.0, v177
	v_add_f32_e32 v178, 1.0, v178
	v_add_f32_e32 v179, 1.0, v179
	v_add_f32_e32 v180, 1.0, v180
	v_add_f32_e32 v181, 1.0, v181
	v_add_f32_e32 v182, 1.0, v182
	v_add_f32_e32 v183, 1.0, v183
	v_rcp_f32_e32 v176, v176
	v_rcp_f32_e32 v177, v177
	v_rcp_f32_e32 v178, v178
	v_rcp_f32_e32 v179, v179
	v_rcp_f32_e32 v180, v180
	v_rcp_f32_e32 v181, v181
	v_rcp_f32_e32 v182, v182
	v_rcp_f32_e32 v183, v183
	v_max_f32_e32 v176, 0x358637bd, v176
	v_max_f32_e32 v177, 0x358637bd, v177
	v_max_f32_e32 v178, 0x358637bd, v178
	v_max_f32_e32 v179, 0x358637bd, v179
	v_max_f32_e32 v180, 0x358637bd, v180
	v_max_f32_e32 v181, 0x358637bd, v181
	v_max_f32_e32 v182, 0x358637bd, v182
	v_max_f32_e32 v183, 0x358637bd, v183
	v_cvt_pk_bf16_f32 v184, v176, v177
	v_cvt_pk_bf16_f32 v185, v178, v179
	v_cvt_pk_bf16_f32 v186, v180, v181
	v_cvt_pk_bf16_f32 v187, v182, v183
	global_store_short v192, v184, s[62:63]
	global_store_short v192, v186, s[62:63] offset:64
	v_add_u32_e32 v192, 0x800, v192
	global_store_short_d16_hi v192, v184, s[62:63]
	global_store_short_d16_hi v192, v186, s[62:63] offset:64
	v_add_u32_e32 v192, 0x800, v192
	global_store_short v192, v185, s[62:63]
	global_store_short v192, v187, s[62:63] offset:64
	v_add_u32_e32 v192, 0x800, v192
	global_store_short_d16_hi v192, v185, s[62:63]
	global_store_short_d16_hi v192, v187, s[62:63] offset:64
	v_add_u32_e32 v192, 0x2800, v192
	s_waitcnt lgkmcnt(7)
	v_mul_f32_e32 v176, v140, v156
	v_mul_f32_e32 v177, v141, v157
	v_mul_f32_e32 v178, v142, v158
	v_mul_f32_e32 v179, v143, v159
	v_mul_f32_e32 v180, v124, v156
	v_mul_f32_e32 v181, v125, v157
	v_mul_f32_e32 v182, v126, v158
	v_mul_f32_e32 v183, v127, v159
	ds_read_b128 v[156:159], v194 offset:352
	v_mul_f32_e32 v176, 0xbfb8aa3b, v176
	v_mul_f32_e32 v177, 0xbfb8aa3b, v177
	v_mul_f32_e32 v178, 0xbfb8aa3b, v178
	v_mul_f32_e32 v179, 0xbfb8aa3b, v179
	v_mul_f32_e32 v180, 0xbfb8aa3b, v180
	v_mul_f32_e32 v181, 0xbfb8aa3b, v181
	v_mul_f32_e32 v182, 0xbfb8aa3b, v182
	v_mul_f32_e32 v183, 0xbfb8aa3b, v183
	v_exp_f32_e32 v176, v176
	v_exp_f32_e32 v177, v177
	v_exp_f32_e32 v178, v178
	v_exp_f32_e32 v179, v179
	v_exp_f32_e32 v180, v180
	v_exp_f32_e32 v181, v181
	v_exp_f32_e32 v182, v182
	v_exp_f32_e32 v183, v183
	v_add_f32_e32 v176, 1.0, v176
	v_add_f32_e32 v177, 1.0, v177
	v_add_f32_e32 v178, 1.0, v178
	v_add_f32_e32 v179, 1.0, v179
	v_add_f32_e32 v180, 1.0, v180
	v_add_f32_e32 v181, 1.0, v181
	v_add_f32_e32 v182, 1.0, v182
	v_add_f32_e32 v183, 1.0, v183
	v_rcp_f32_e32 v176, v176
	v_rcp_f32_e32 v177, v177
	v_rcp_f32_e32 v178, v178
	v_rcp_f32_e32 v179, v179
	v_rcp_f32_e32 v180, v180
	v_rcp_f32_e32 v181, v181
	v_rcp_f32_e32 v182, v182
	v_rcp_f32_e32 v183, v183
	v_max_f32_e32 v176, 0x358637bd, v176
	v_max_f32_e32 v177, 0x358637bd, v177
	v_max_f32_e32 v178, 0x358637bd, v178
	v_max_f32_e32 v179, 0x358637bd, v179
	v_max_f32_e32 v180, 0x358637bd, v180
	v_max_f32_e32 v181, 0x358637bd, v181
	v_max_f32_e32 v182, 0x358637bd, v182
	v_max_f32_e32 v183, 0x358637bd, v183
	v_cvt_pk_bf16_f32 v188, v176, v177
	v_cvt_pk_bf16_f32 v189, v178, v179
	v_cvt_pk_bf16_f32 v190, v180, v181
	v_cvt_pk_bf16_f32 v191, v182, v183
	global_store_short v192, v188, s[62:63]
	global_store_short v192, v190, s[62:63] offset:64
	v_add_u32_e32 v192, 0x800, v192
	global_store_short_d16_hi v192, v188, s[62:63]
	global_store_short_d16_hi v192, v190, s[62:63] offset:64
	v_add_u32_e32 v192, 0x800, v192
	global_store_short v192, v189, s[62:63]
	global_store_short v192, v191, s[62:63] offset:64
	v_add_u32_e32 v192, 0x800, v192
	global_store_short_d16_hi v192, v189, s[62:63]
	global_store_short_d16_hi v192, v191, s[62:63] offset:64
	v_add_u32_e32 v192, 0x2800, v192
	s_waitcnt lgkmcnt(7)
	v_mul_f32_e32 v176, v96, v160
	v_mul_f32_e32 v177, v97, v161
	v_mul_f32_e32 v178, v98, v162
	v_mul_f32_e32 v179, v99, v163
	v_mul_f32_e32 v180, v64, v160
	v_mul_f32_e32 v181, v65, v161
	v_mul_f32_e32 v182, v66, v162
	v_mul_f32_e32 v183, v67, v163
	ds_read_b128 v[160:163], v194 offset:384
	v_mul_f32_e32 v176, 0xbfb8aa3b, v176
	v_mul_f32_e32 v177, 0xbfb8aa3b, v177
	v_mul_f32_e32 v178, 0xbfb8aa3b, v178
	v_mul_f32_e32 v179, 0xbfb8aa3b, v179
	v_mul_f32_e32 v180, 0xbfb8aa3b, v180
	v_mul_f32_e32 v181, 0xbfb8aa3b, v181
	v_mul_f32_e32 v182, 0xbfb8aa3b, v182
	v_mul_f32_e32 v183, 0xbfb8aa3b, v183
	v_exp_f32_e32 v176, v176
	v_exp_f32_e32 v177, v177
	v_exp_f32_e32 v178, v178
	v_exp_f32_e32 v179, v179
	v_exp_f32_e32 v180, v180
	v_exp_f32_e32 v181, v181
	v_exp_f32_e32 v182, v182
	v_exp_f32_e32 v183, v183
	v_add_f32_e32 v176, 1.0, v176
	v_add_f32_e32 v177, 1.0, v177
	v_add_f32_e32 v178, 1.0, v178
	v_add_f32_e32 v179, 1.0, v179
	v_add_f32_e32 v180, 1.0, v180
	v_add_f32_e32 v181, 1.0, v181
	v_add_f32_e32 v182, 1.0, v182
	v_add_f32_e32 v183, 1.0, v183
	v_rcp_f32_e32 v176, v176
	v_rcp_f32_e32 v177, v177
	v_rcp_f32_e32 v178, v178
	v_rcp_f32_e32 v179, v179
	v_rcp_f32_e32 v180, v180
	v_rcp_f32_e32 v181, v181
	v_rcp_f32_e32 v182, v182
	v_rcp_f32_e32 v183, v183
	v_max_f32_e32 v176, 0x358637bd, v176
	v_max_f32_e32 v177, 0x358637bd, v177
	v_max_f32_e32 v178, 0x358637bd, v178
	v_max_f32_e32 v179, 0x358637bd, v179
	v_max_f32_e32 v180, 0x358637bd, v180
	v_max_f32_e32 v181, 0x358637bd, v181
	v_max_f32_e32 v182, 0x358637bd, v182
	v_max_f32_e32 v183, 0x358637bd, v183
	v_cvt_pk_bf16_f32 v184, v176, v177
	v_cvt_pk_bf16_f32 v185, v178, v179
	v_cvt_pk_bf16_f32 v186, v180, v181
	v_cvt_pk_bf16_f32 v187, v182, v183
	global_store_short v192, v184, s[62:63]
	global_store_short v192, v186, s[62:63] offset:64
	v_add_u32_e32 v192, 0x800, v192
	global_store_short_d16_hi v192, v184, s[62:63]
	global_store_short_d16_hi v192, v186, s[62:63] offset:64
	v_add_u32_e32 v192, 0x800, v192
	global_store_short v192, v185, s[62:63]
	global_store_short v192, v187, s[62:63] offset:64
	v_add_u32_e32 v192, 0x800, v192
	global_store_short_d16_hi v192, v185, s[62:63]
	global_store_short_d16_hi v192, v187, s[62:63] offset:64
	v_add_u32_e32 v192, 0x2800, v192
	s_waitcnt lgkmcnt(7)
	v_mul_f32_e32 v176, v100, v164
	v_mul_f32_e32 v177, v101, v165
	v_mul_f32_e32 v178, v102, v166
	v_mul_f32_e32 v179, v103, v167
	v_mul_f32_e32 v180, v68, v164
	v_mul_f32_e32 v181, v69, v165
	v_mul_f32_e32 v182, v70, v166
	v_mul_f32_e32 v183, v71, v167
	ds_read_b128 v[164:167], v194 offset:416
	v_mul_f32_e32 v176, 0xbfb8aa3b, v176
	v_mul_f32_e32 v177, 0xbfb8aa3b, v177
	v_mul_f32_e32 v178, 0xbfb8aa3b, v178
	v_mul_f32_e32 v179, 0xbfb8aa3b, v179
	v_mul_f32_e32 v180, 0xbfb8aa3b, v180
	v_mul_f32_e32 v181, 0xbfb8aa3b, v181
	v_mul_f32_e32 v182, 0xbfb8aa3b, v182
	v_mul_f32_e32 v183, 0xbfb8aa3b, v183
	v_exp_f32_e32 v176, v176
	v_exp_f32_e32 v177, v177
	v_exp_f32_e32 v178, v178
	v_exp_f32_e32 v179, v179
	v_exp_f32_e32 v180, v180
	v_exp_f32_e32 v181, v181
	v_exp_f32_e32 v182, v182
	v_exp_f32_e32 v183, v183
	v_add_f32_e32 v176, 1.0, v176
	v_add_f32_e32 v177, 1.0, v177
	v_add_f32_e32 v178, 1.0, v178
	v_add_f32_e32 v179, 1.0, v179
	v_add_f32_e32 v180, 1.0, v180
	v_add_f32_e32 v181, 1.0, v181
	v_add_f32_e32 v182, 1.0, v182
	v_add_f32_e32 v183, 1.0, v183
	v_rcp_f32_e32 v176, v176
	v_rcp_f32_e32 v177, v177
	v_rcp_f32_e32 v178, v178
	v_rcp_f32_e32 v179, v179
	v_rcp_f32_e32 v180, v180
	v_rcp_f32_e32 v181, v181
	v_rcp_f32_e32 v182, v182
	v_rcp_f32_e32 v183, v183
	v_max_f32_e32 v176, 0x358637bd, v176
	v_max_f32_e32 v177, 0x358637bd, v177
	v_max_f32_e32 v178, 0x358637bd, v178
	v_max_f32_e32 v179, 0x358637bd, v179
	v_max_f32_e32 v180, 0x358637bd, v180
	v_max_f32_e32 v181, 0x358637bd, v181
	v_max_f32_e32 v182, 0x358637bd, v182
	v_max_f32_e32 v183, 0x358637bd, v183
	v_cvt_pk_bf16_f32 v188, v176, v177
	v_cvt_pk_bf16_f32 v189, v178, v179
	v_cvt_pk_bf16_f32 v190, v180, v181
	v_cvt_pk_bf16_f32 v191, v182, v183
	global_store_short v192, v188, s[62:63]
	global_store_short v192, v190, s[62:63] offset:64
	v_add_u32_e32 v192, 0x800, v192
	global_store_short_d16_hi v192, v188, s[62:63]
	global_store_short_d16_hi v192, v190, s[62:63] offset:64
	v_add_u32_e32 v192, 0x800, v192
	global_store_short v192, v189, s[62:63]
	global_store_short v192, v191, s[62:63] offset:64
	v_add_u32_e32 v192, 0x800, v192
	global_store_short_d16_hi v192, v189, s[62:63]
	global_store_short_d16_hi v192, v191, s[62:63] offset:64
	v_add_u32_e32 v192, 0x2800, v192
	s_waitcnt lgkmcnt(7)
	v_mul_f32_e32 v176, v104, v168
	v_mul_f32_e32 v177, v105, v169
	v_mul_f32_e32 v178, v106, v170
	v_mul_f32_e32 v179, v107, v171
	v_mul_f32_e32 v180, v72, v168
	v_mul_f32_e32 v181, v73, v169
	v_mul_f32_e32 v182, v74, v170
	v_mul_f32_e32 v183, v75, v171
	ds_read_b128 v[168:171], v194 offset:448
	v_mul_f32_e32 v176, 0xbfb8aa3b, v176
	v_mul_f32_e32 v177, 0xbfb8aa3b, v177
	v_mul_f32_e32 v178, 0xbfb8aa3b, v178
	v_mul_f32_e32 v179, 0xbfb8aa3b, v179
	v_mul_f32_e32 v180, 0xbfb8aa3b, v180
	v_mul_f32_e32 v181, 0xbfb8aa3b, v181
	v_mul_f32_e32 v182, 0xbfb8aa3b, v182
	v_mul_f32_e32 v183, 0xbfb8aa3b, v183
	v_exp_f32_e32 v176, v176
	v_exp_f32_e32 v177, v177
	v_exp_f32_e32 v178, v178
	v_exp_f32_e32 v179, v179
	v_exp_f32_e32 v180, v180
	v_exp_f32_e32 v181, v181
	v_exp_f32_e32 v182, v182
	v_exp_f32_e32 v183, v183
	v_add_f32_e32 v176, 1.0, v176
	v_add_f32_e32 v177, 1.0, v177
	v_add_f32_e32 v178, 1.0, v178
	v_add_f32_e32 v179, 1.0, v179
	v_add_f32_e32 v180, 1.0, v180
	v_add_f32_e32 v181, 1.0, v181
	v_add_f32_e32 v182, 1.0, v182
	v_add_f32_e32 v183, 1.0, v183
	v_rcp_f32_e32 v176, v176
	v_rcp_f32_e32 v177, v177
	v_rcp_f32_e32 v178, v178
	v_rcp_f32_e32 v179, v179
	v_rcp_f32_e32 v180, v180
	v_rcp_f32_e32 v181, v181
	v_rcp_f32_e32 v182, v182
	v_rcp_f32_e32 v183, v183
	v_max_f32_e32 v176, 0x358637bd, v176
	v_max_f32_e32 v177, 0x358637bd, v177
	v_max_f32_e32 v178, 0x358637bd, v178
	v_max_f32_e32 v179, 0x358637bd, v179
	v_max_f32_e32 v180, 0x358637bd, v180
	v_max_f32_e32 v181, 0x358637bd, v181
	v_max_f32_e32 v182, 0x358637bd, v182
	v_max_f32_e32 v183, 0x358637bd, v183
	v_cvt_pk_bf16_f32 v184, v176, v177
	v_cvt_pk_bf16_f32 v185, v178, v179
	v_cvt_pk_bf16_f32 v186, v180, v181
	v_cvt_pk_bf16_f32 v187, v182, v183
	global_store_short v192, v184, s[62:63]
	global_store_short v192, v186, s[62:63] offset:64
	v_add_u32_e32 v192, 0x800, v192
	global_store_short_d16_hi v192, v184, s[62:63]
	global_store_short_d16_hi v192, v186, s[62:63] offset:64
	v_add_u32_e32 v192, 0x800, v192
	global_store_short v192, v185, s[62:63]
	global_store_short v192, v187, s[62:63] offset:64
	v_add_u32_e32 v192, 0x800, v192
	global_store_short_d16_hi v192, v185, s[62:63]
	global_store_short_d16_hi v192, v187, s[62:63] offset:64
	v_add_u32_e32 v192, 0x2800, v192
	s_waitcnt lgkmcnt(7)
	v_mul_f32_e32 v176, v108, v172
	v_mul_f32_e32 v177, v109, v173
	v_mul_f32_e32 v178, v110, v174
	v_mul_f32_e32 v179, v111, v175
	v_mul_f32_e32 v180, v76, v172
	v_mul_f32_e32 v181, v77, v173
	v_mul_f32_e32 v182, v78, v174
	v_mul_f32_e32 v183, v79, v175
	ds_read_b128 v[172:175], v194 offset:480
	v_mul_f32_e32 v176, 0xbfb8aa3b, v176
	v_mul_f32_e32 v177, 0xbfb8aa3b, v177
	v_mul_f32_e32 v178, 0xbfb8aa3b, v178
	v_mul_f32_e32 v179, 0xbfb8aa3b, v179
	v_mul_f32_e32 v180, 0xbfb8aa3b, v180
	v_mul_f32_e32 v181, 0xbfb8aa3b, v181
	v_mul_f32_e32 v182, 0xbfb8aa3b, v182
	v_mul_f32_e32 v183, 0xbfb8aa3b, v183
	v_exp_f32_e32 v176, v176
	v_exp_f32_e32 v177, v177
	v_exp_f32_e32 v178, v178
	v_exp_f32_e32 v179, v179
	v_exp_f32_e32 v180, v180
	v_exp_f32_e32 v181, v181
	v_exp_f32_e32 v182, v182
	v_exp_f32_e32 v183, v183
	v_add_f32_e32 v176, 1.0, v176
	v_add_f32_e32 v177, 1.0, v177
	v_add_f32_e32 v178, 1.0, v178
	v_add_f32_e32 v179, 1.0, v179
	v_add_f32_e32 v180, 1.0, v180
	v_add_f32_e32 v181, 1.0, v181
	v_add_f32_e32 v182, 1.0, v182
	v_add_f32_e32 v183, 1.0, v183
	v_rcp_f32_e32 v176, v176
	v_rcp_f32_e32 v177, v177
	v_rcp_f32_e32 v178, v178
	v_rcp_f32_e32 v179, v179
	v_rcp_f32_e32 v180, v180
	v_rcp_f32_e32 v181, v181
	v_rcp_f32_e32 v182, v182
	v_rcp_f32_e32 v183, v183
	v_max_f32_e32 v176, 0x358637bd, v176
	v_max_f32_e32 v177, 0x358637bd, v177
	v_max_f32_e32 v178, 0x358637bd, v178
	v_max_f32_e32 v179, 0x358637bd, v179
	v_max_f32_e32 v180, 0x358637bd, v180
	v_max_f32_e32 v181, 0x358637bd, v181
	v_max_f32_e32 v182, 0x358637bd, v182
	v_max_f32_e32 v183, 0x358637bd, v183
	v_cvt_pk_bf16_f32 v188, v176, v177
	v_cvt_pk_bf16_f32 v189, v178, v179
	v_cvt_pk_bf16_f32 v190, v180, v181
	v_cvt_pk_bf16_f32 v191, v182, v183
	global_store_short v192, v188, s[62:63]
	global_store_short v192, v190, s[62:63] offset:64
	v_add_u32_e32 v192, 0x800, v192
	global_store_short_d16_hi v192, v188, s[62:63]
	global_store_short_d16_hi v192, v190, s[62:63] offset:64
	v_add_u32_e32 v192, 0x800, v192
	global_store_short v192, v189, s[62:63]
	global_store_short v192, v191, s[62:63] offset:64
	v_add_u32_e32 v192, 0x800, v192
	global_store_short_d16_hi v192, v189, s[62:63]
	global_store_short_d16_hi v192, v191, s[62:63] offset:64
	v_add_u32_e32 v192, 0x2800, v192
	s_cmpk_lt_i32 s8, 0x4000
	s_cbranch_scc1 .Lp6x_e2_c
	s_waitcnt lgkmcnt(0)
	s_branch .Lp6x_e2_e
.Lp6x_e2_c:
	s_waitcnt lgkmcnt(7)
	v_mul_f32_e32 v176, v80, v144
	v_mul_f32_e32 v177, v81, v145
	v_mul_f32_e32 v178, v82, v146
	v_mul_f32_e32 v179, v83, v147
	v_mul_f32_e32 v180, v48, v144
	v_mul_f32_e32 v181, v49, v145
	v_mul_f32_e32 v182, v50, v146
	v_mul_f32_e32 v183, v51, v147
	v_mul_f32_e32 v176, 0xbfb8aa3b, v176
	v_mul_f32_e32 v177, 0xbfb8aa3b, v177
	v_mul_f32_e32 v178, 0xbfb8aa3b, v178
	v_mul_f32_e32 v179, 0xbfb8aa3b, v179
	v_mul_f32_e32 v180, 0xbfb8aa3b, v180
	v_mul_f32_e32 v181, 0xbfb8aa3b, v181
	v_mul_f32_e32 v182, 0xbfb8aa3b, v182
	v_mul_f32_e32 v183, 0xbfb8aa3b, v183
	v_exp_f32_e32 v176, v176
	v_exp_f32_e32 v177, v177
	v_exp_f32_e32 v178, v178
	v_exp_f32_e32 v179, v179
	v_exp_f32_e32 v180, v180
	v_exp_f32_e32 v181, v181
	v_exp_f32_e32 v182, v182
	v_exp_f32_e32 v183, v183
	v_add_f32_e32 v176, 1.0, v176
	v_add_f32_e32 v177, 1.0, v177
	v_add_f32_e32 v178, 1.0, v178
	v_add_f32_e32 v179, 1.0, v179
	v_add_f32_e32 v180, 1.0, v180
	v_add_f32_e32 v181, 1.0, v181
	v_add_f32_e32 v182, 1.0, v182
	v_add_f32_e32 v183, 1.0, v183
	v_rcp_f32_e32 v176, v176
	v_rcp_f32_e32 v177, v177
	v_rcp_f32_e32 v178, v178
	v_rcp_f32_e32 v179, v179
	v_rcp_f32_e32 v180, v180
	v_rcp_f32_e32 v181, v181
	v_rcp_f32_e32 v182, v182
	v_rcp_f32_e32 v183, v183
	v_max_f32_e32 v176, 0x358637bd, v176
	v_max_f32_e32 v177, 0x358637bd, v177
	v_max_f32_e32 v178, 0x358637bd, v178
	v_max_f32_e32 v179, 0x358637bd, v179
	v_max_f32_e32 v180, 0x358637bd, v180
	v_max_f32_e32 v181, 0x358637bd, v181
	v_max_f32_e32 v182, 0x358637bd, v182
	v_max_f32_e32 v183, 0x358637bd, v183
	v_cvt_pk_bf16_f32 v184, v176, v177
	v_cvt_pk_bf16_f32 v185, v178, v179
	v_cvt_pk_bf16_f32 v186, v180, v181
	v_cvt_pk_bf16_f32 v187, v182, v183
	global_store_short v192, v184, s[62:63]
	global_store_short v192, v186, s[62:63] offset:64
	v_add_u32_e32 v192, 0x800, v192
	global_store_short_d16_hi v192, v184, s[62:63]
	global_store_short_d16_hi v192, v186, s[62:63] offset:64
	v_add_u32_e32 v192, 0x800, v192
	global_store_short v192, v185, s[62:63]
	global_store_short v192, v187, s[62:63] offset:64
	v_add_u32_e32 v192, 0x800, v192
	global_store_short_d16_hi v192, v185, s[62:63]
	global_store_short_d16_hi v192, v187, s[62:63] offset:64
	v_add_u32_e32 v192, 0x2800, v192
	s_waitcnt lgkmcnt(6)
	v_mul_f32_e32 v176, v84, v148
	v_mul_f32_e32 v177, v85, v149
	v_mul_f32_e32 v178, v86, v150
	v_mul_f32_e32 v179, v87, v151
	v_mul_f32_e32 v180, v52, v148
	v_mul_f32_e32 v181, v53, v149
	v_mul_f32_e32 v182, v54, v150
	v_mul_f32_e32 v183, v55, v151
	v_mul_f32_e32 v176, 0xbfb8aa3b, v176
	v_mul_f32_e32 v177, 0xbfb8aa3b, v177
	v_mul_f32_e32 v178, 0xbfb8aa3b, v178
	v_mul_f32_e32 v179, 0xbfb8aa3b, v179
	v_mul_f32_e32 v180, 0xbfb8aa3b, v180
	v_mul_f32_e32 v181, 0xbfb8aa3b, v181
	v_mul_f32_e32 v182, 0xbfb8aa3b, v182
	v_mul_f32_e32 v183, 0xbfb8aa3b, v183
	v_exp_f32_e32 v176, v176
	v_exp_f32_e32 v177, v177
	v_exp_f32_e32 v178, v178
	v_exp_f32_e32 v179, v179
	v_exp_f32_e32 v180, v180
	v_exp_f32_e32 v181, v181
	v_exp_f32_e32 v182, v182
	v_exp_f32_e32 v183, v183
	v_add_f32_e32 v176, 1.0, v176
	v_add_f32_e32 v177, 1.0, v177
	v_add_f32_e32 v178, 1.0, v178
	v_add_f32_e32 v179, 1.0, v179
	v_add_f32_e32 v180, 1.0, v180
	v_add_f32_e32 v181, 1.0, v181
	v_add_f32_e32 v182, 1.0, v182
	v_add_f32_e32 v183, 1.0, v183
	v_rcp_f32_e32 v176, v176
	v_rcp_f32_e32 v177, v177
	v_rcp_f32_e32 v178, v178
	v_rcp_f32_e32 v179, v179
	v_rcp_f32_e32 v180, v180
	v_rcp_f32_e32 v181, v181
	v_rcp_f32_e32 v182, v182
	v_rcp_f32_e32 v183, v183
	v_max_f32_e32 v176, 0x358637bd, v176
	v_max_f32_e32 v177, 0x358637bd, v177
	v_max_f32_e32 v178, 0x358637bd, v178
	v_max_f32_e32 v179, 0x358637bd, v179
	v_max_f32_e32 v180, 0x358637bd, v180
	v_max_f32_e32 v181, 0x358637bd, v181
	v_max_f32_e32 v182, 0x358637bd, v182
	v_max_f32_e32 v183, 0x358637bd, v183
	v_cvt_pk_bf16_f32 v188, v176, v177
	v_cvt_pk_bf16_f32 v189, v178, v179
	v_cvt_pk_bf16_f32 v190, v180, v181
	v_cvt_pk_bf16_f32 v191, v182, v183
	global_store_short v192, v188, s[62:63]
	global_store_short v192, v190, s[62:63] offset:64
	v_add_u32_e32 v192, 0x800, v192
	global_store_short_d16_hi v192, v188, s[62:63]
	global_store_short_d16_hi v192, v190, s[62:63] offset:64
	v_add_u32_e32 v192, 0x800, v192
	global_store_short v192, v189, s[62:63]
	global_store_short v192, v191, s[62:63] offset:64
	v_add_u32_e32 v192, 0x800, v192
	global_store_short_d16_hi v192, v189, s[62:63]
	global_store_short_d16_hi v192, v191, s[62:63] offset:64
	v_add_u32_e32 v192, 0x2800, v192
	s_waitcnt lgkmcnt(5)
	v_mul_f32_e32 v176, v88, v152
	v_mul_f32_e32 v177, v89, v153
	v_mul_f32_e32 v178, v90, v154
	v_mul_f32_e32 v179, v91, v155
	v_mul_f32_e32 v180, v56, v152
	v_mul_f32_e32 v181, v57, v153
	v_mul_f32_e32 v182, v58, v154
	v_mul_f32_e32 v183, v59, v155
	v_mul_f32_e32 v176, 0xbfb8aa3b, v176
	v_mul_f32_e32 v177, 0xbfb8aa3b, v177
	v_mul_f32_e32 v178, 0xbfb8aa3b, v178
	v_mul_f32_e32 v179, 0xbfb8aa3b, v179
	v_mul_f32_e32 v180, 0xbfb8aa3b, v180
	v_mul_f32_e32 v181, 0xbfb8aa3b, v181
	v_mul_f32_e32 v182, 0xbfb8aa3b, v182
	v_mul_f32_e32 v183, 0xbfb8aa3b, v183
	v_exp_f32_e32 v176, v176
	v_exp_f32_e32 v177, v177
	v_exp_f32_e32 v178, v178
	v_exp_f32_e32 v179, v179
	v_exp_f32_e32 v180, v180
	v_exp_f32_e32 v181, v181
	v_exp_f32_e32 v182, v182
	v_exp_f32_e32 v183, v183
	v_add_f32_e32 v176, 1.0, v176
	v_add_f32_e32 v177, 1.0, v177
	v_add_f32_e32 v178, 1.0, v178
	v_add_f32_e32 v179, 1.0, v179
	v_add_f32_e32 v180, 1.0, v180
	v_add_f32_e32 v181, 1.0, v181
	v_add_f32_e32 v182, 1.0, v182
	v_add_f32_e32 v183, 1.0, v183
	v_rcp_f32_e32 v176, v176
	v_rcp_f32_e32 v177, v177
	v_rcp_f32_e32 v178, v178
	v_rcp_f32_e32 v179, v179
	v_rcp_f32_e32 v180, v180
	v_rcp_f32_e32 v181, v181
	v_rcp_f32_e32 v182, v182
	v_rcp_f32_e32 v183, v183
	v_max_f32_e32 v176, 0x358637bd, v176
	v_max_f32_e32 v177, 0x358637bd, v177
	v_max_f32_e32 v178, 0x358637bd, v178
	v_max_f32_e32 v179, 0x358637bd, v179
	v_max_f32_e32 v180, 0x358637bd, v180
	v_max_f32_e32 v181, 0x358637bd, v181
	v_max_f32_e32 v182, 0x358637bd, v182
	v_max_f32_e32 v183, 0x358637bd, v183
	v_cvt_pk_bf16_f32 v184, v176, v177
	v_cvt_pk_bf16_f32 v185, v178, v179
	v_cvt_pk_bf16_f32 v186, v180, v181
	v_cvt_pk_bf16_f32 v187, v182, v183
	global_store_short v192, v184, s[62:63]
	global_store_short v192, v186, s[62:63] offset:64
	v_add_u32_e32 v192, 0x800, v192
	global_store_short_d16_hi v192, v184, s[62:63]
	global_store_short_d16_hi v192, v186, s[62:63] offset:64
	v_add_u32_e32 v192, 0x800, v192
	global_store_short v192, v185, s[62:63]
	global_store_short v192, v187, s[62:63] offset:64
	v_add_u32_e32 v192, 0x800, v192
	global_store_short_d16_hi v192, v185, s[62:63]
	global_store_short_d16_hi v192, v187, s[62:63] offset:64
	v_add_u32_e32 v192, 0x2800, v192
	s_waitcnt lgkmcnt(4)
	v_mul_f32_e32 v176, v92, v156
	v_mul_f32_e32 v177, v93, v157
	v_mul_f32_e32 v178, v94, v158
	v_mul_f32_e32 v179, v95, v159
	v_mul_f32_e32 v180, v60, v156
	v_mul_f32_e32 v181, v61, v157
	v_mul_f32_e32 v182, v62, v158
	v_mul_f32_e32 v183, v63, v159
	v_mul_f32_e32 v176, 0xbfb8aa3b, v176
	v_mul_f32_e32 v177, 0xbfb8aa3b, v177
	v_mul_f32_e32 v178, 0xbfb8aa3b, v178
	v_mul_f32_e32 v179, 0xbfb8aa3b, v179
	v_mul_f32_e32 v180, 0xbfb8aa3b, v180
	v_mul_f32_e32 v181, 0xbfb8aa3b, v181
	v_mul_f32_e32 v182, 0xbfb8aa3b, v182
	v_mul_f32_e32 v183, 0xbfb8aa3b, v183
	v_exp_f32_e32 v176, v176
	v_exp_f32_e32 v177, v177
	v_exp_f32_e32 v178, v178
	v_exp_f32_e32 v179, v179
	v_exp_f32_e32 v180, v180
	v_exp_f32_e32 v181, v181
	v_exp_f32_e32 v182, v182
	v_exp_f32_e32 v183, v183
	v_add_f32_e32 v176, 1.0, v176
	v_add_f32_e32 v177, 1.0, v177
	v_add_f32_e32 v178, 1.0, v178
	v_add_f32_e32 v179, 1.0, v179
	v_add_f32_e32 v180, 1.0, v180
	v_add_f32_e32 v181, 1.0, v181
	v_add_f32_e32 v182, 1.0, v182
	v_add_f32_e32 v183, 1.0, v183
	v_rcp_f32_e32 v176, v176
	v_rcp_f32_e32 v177, v177
	v_rcp_f32_e32 v178, v178
	v_rcp_f32_e32 v179, v179
	v_rcp_f32_e32 v180, v180
	v_rcp_f32_e32 v181, v181
	v_rcp_f32_e32 v182, v182
	v_rcp_f32_e32 v183, v183
	v_max_f32_e32 v176, 0x358637bd, v176
	v_max_f32_e32 v177, 0x358637bd, v177
	v_max_f32_e32 v178, 0x358637bd, v178
	v_max_f32_e32 v179, 0x358637bd, v179
	v_max_f32_e32 v180, 0x358637bd, v180
	v_max_f32_e32 v181, 0x358637bd, v181
	v_max_f32_e32 v182, 0x358637bd, v182
	v_max_f32_e32 v183, 0x358637bd, v183
	v_cvt_pk_bf16_f32 v188, v176, v177
	v_cvt_pk_bf16_f32 v189, v178, v179
	v_cvt_pk_bf16_f32 v190, v180, v181
	v_cvt_pk_bf16_f32 v191, v182, v183
	global_store_short v192, v188, s[62:63]
	global_store_short v192, v190, s[62:63] offset:64
	v_add_u32_e32 v192, 0x800, v192
	global_store_short_d16_hi v192, v188, s[62:63]
	global_store_short_d16_hi v192, v190, s[62:63] offset:64
	v_add_u32_e32 v192, 0x800, v192
	global_store_short v192, v189, s[62:63]
	global_store_short v192, v191, s[62:63] offset:64
	v_add_u32_e32 v192, 0x800, v192
	global_store_short_d16_hi v192, v189, s[62:63]
	global_store_short_d16_hi v192, v191, s[62:63] offset:64
	v_add_u32_e32 v192, 0x2800, v192
	s_waitcnt lgkmcnt(3)
	v_mul_f32_e32 v176, v32, v160
	v_mul_f32_e32 v177, v33, v161
	v_mul_f32_e32 v178, v34, v162
	v_mul_f32_e32 v179, v35, v163
	v_mul_f32_e32 v180, v16, v160
	v_mul_f32_e32 v181, v17, v161
	v_mul_f32_e32 v182, v18, v162
	v_mul_f32_e32 v183, v19, v163
	v_mul_f32_e32 v176, 0xbfb8aa3b, v176
	v_mul_f32_e32 v177, 0xbfb8aa3b, v177
	v_mul_f32_e32 v178, 0xbfb8aa3b, v178
	v_mul_f32_e32 v179, 0xbfb8aa3b, v179
	v_mul_f32_e32 v180, 0xbfb8aa3b, v180
	v_mul_f32_e32 v181, 0xbfb8aa3b, v181
	v_mul_f32_e32 v182, 0xbfb8aa3b, v182
	v_mul_f32_e32 v183, 0xbfb8aa3b, v183
	v_exp_f32_e32 v176, v176
	v_exp_f32_e32 v177, v177
	v_exp_f32_e32 v178, v178
	v_exp_f32_e32 v179, v179
	v_exp_f32_e32 v180, v180
	v_exp_f32_e32 v181, v181
	v_exp_f32_e32 v182, v182
	v_exp_f32_e32 v183, v183
	v_add_f32_e32 v176, 1.0, v176
	v_add_f32_e32 v177, 1.0, v177
	v_add_f32_e32 v178, 1.0, v178
	v_add_f32_e32 v179, 1.0, v179
	v_add_f32_e32 v180, 1.0, v180
	v_add_f32_e32 v181, 1.0, v181
	v_add_f32_e32 v182, 1.0, v182
	v_add_f32_e32 v183, 1.0, v183
	v_rcp_f32_e32 v176, v176
	v_rcp_f32_e32 v177, v177
	v_rcp_f32_e32 v178, v178
	v_rcp_f32_e32 v179, v179
	v_rcp_f32_e32 v180, v180
	v_rcp_f32_e32 v181, v181
	v_rcp_f32_e32 v182, v182
	v_rcp_f32_e32 v183, v183
	v_max_f32_e32 v176, 0x358637bd, v176
	v_max_f32_e32 v177, 0x358637bd, v177
	v_max_f32_e32 v178, 0x358637bd, v178
	v_max_f32_e32 v179, 0x358637bd, v179
	v_max_f32_e32 v180, 0x358637bd, v180
	v_max_f32_e32 v181, 0x358637bd, v181
	v_max_f32_e32 v182, 0x358637bd, v182
	v_max_f32_e32 v183, 0x358637bd, v183
	v_cvt_pk_bf16_f32 v184, v176, v177
	v_cvt_pk_bf16_f32 v185, v178, v179
	v_cvt_pk_bf16_f32 v186, v180, v181
	v_cvt_pk_bf16_f32 v187, v182, v183
	global_store_short v192, v184, s[62:63]
	global_store_short v192, v186, s[62:63] offset:64
	v_add_u32_e32 v192, 0x800, v192
	global_store_short_d16_hi v192, v184, s[62:63]
	global_store_short_d16_hi v192, v186, s[62:63] offset:64
	v_add_u32_e32 v192, 0x800, v192
	global_store_short v192, v185, s[62:63]
	global_store_short v192, v187, s[62:63] offset:64
	v_add_u32_e32 v192, 0x800, v192
	global_store_short_d16_hi v192, v185, s[62:63]
	global_store_short_d16_hi v192, v187, s[62:63] offset:64
	v_add_u32_e32 v192, 0x2800, v192
	s_waitcnt lgkmcnt(2)
	v_mul_f32_e32 v176, v36, v164
	v_mul_f32_e32 v177, v37, v165
	v_mul_f32_e32 v178, v38, v166
	v_mul_f32_e32 v179, v39, v167
	v_mul_f32_e32 v180, v20, v164
	v_mul_f32_e32 v181, v21, v165
	v_mul_f32_e32 v182, v22, v166
	v_mul_f32_e32 v183, v23, v167
	v_mul_f32_e32 v176, 0xbfb8aa3b, v176
	v_mul_f32_e32 v177, 0xbfb8aa3b, v177
	v_mul_f32_e32 v178, 0xbfb8aa3b, v178
	v_mul_f32_e32 v179, 0xbfb8aa3b, v179
	v_mul_f32_e32 v180, 0xbfb8aa3b, v180
	v_mul_f32_e32 v181, 0xbfb8aa3b, v181
	v_mul_f32_e32 v182, 0xbfb8aa3b, v182
	v_mul_f32_e32 v183, 0xbfb8aa3b, v183
	v_exp_f32_e32 v176, v176
	v_exp_f32_e32 v177, v177
	v_exp_f32_e32 v178, v178
	v_exp_f32_e32 v179, v179
	v_exp_f32_e32 v180, v180
	v_exp_f32_e32 v181, v181
	v_exp_f32_e32 v182, v182
	v_exp_f32_e32 v183, v183
	v_add_f32_e32 v176, 1.0, v176
	v_add_f32_e32 v177, 1.0, v177
	v_add_f32_e32 v178, 1.0, v178
	v_add_f32_e32 v179, 1.0, v179
	v_add_f32_e32 v180, 1.0, v180
	v_add_f32_e32 v181, 1.0, v181
	v_add_f32_e32 v182, 1.0, v182
	v_add_f32_e32 v183, 1.0, v183
	v_rcp_f32_e32 v176, v176
	v_rcp_f32_e32 v177, v177
	v_rcp_f32_e32 v178, v178
	v_rcp_f32_e32 v179, v179
	v_rcp_f32_e32 v180, v180
	v_rcp_f32_e32 v181, v181
	v_rcp_f32_e32 v182, v182
	v_rcp_f32_e32 v183, v183
	v_max_f32_e32 v176, 0x358637bd, v176
	v_max_f32_e32 v177, 0x358637bd, v177
	v_max_f32_e32 v178, 0x358637bd, v178
	v_max_f32_e32 v179, 0x358637bd, v179
	v_max_f32_e32 v180, 0x358637bd, v180
	v_max_f32_e32 v181, 0x358637bd, v181
	v_max_f32_e32 v182, 0x358637bd, v182
	v_max_f32_e32 v183, 0x358637bd, v183
	v_cvt_pk_bf16_f32 v188, v176, v177
	v_cvt_pk_bf16_f32 v189, v178, v179
	v_cvt_pk_bf16_f32 v190, v180, v181
	v_cvt_pk_bf16_f32 v191, v182, v183
	global_store_short v192, v188, s[62:63]
	global_store_short v192, v190, s[62:63] offset:64
	v_add_u32_e32 v192, 0x800, v192
	global_store_short_d16_hi v192, v188, s[62:63]
	global_store_short_d16_hi v192, v190, s[62:63] offset:64
	v_add_u32_e32 v192, 0x800, v192
	global_store_short v192, v189, s[62:63]
	global_store_short v192, v191, s[62:63] offset:64
	v_add_u32_e32 v192, 0x800, v192
	global_store_short_d16_hi v192, v189, s[62:63]
	global_store_short_d16_hi v192, v191, s[62:63] offset:64
	v_add_u32_e32 v192, 0x2800, v192
	s_waitcnt lgkmcnt(1)
	v_mul_f32_e32 v176, v40, v168
	v_mul_f32_e32 v177, v41, v169
	v_mul_f32_e32 v178, v42, v170
	v_mul_f32_e32 v179, v43, v171
	v_mul_f32_e32 v180, v24, v168
	v_mul_f32_e32 v181, v25, v169
	v_mul_f32_e32 v182, v26, v170
	v_mul_f32_e32 v183, v27, v171
	v_mul_f32_e32 v176, 0xbfb8aa3b, v176
	v_mul_f32_e32 v177, 0xbfb8aa3b, v177
	v_mul_f32_e32 v178, 0xbfb8aa3b, v178
	v_mul_f32_e32 v179, 0xbfb8aa3b, v179
	v_mul_f32_e32 v180, 0xbfb8aa3b, v180
	v_mul_f32_e32 v181, 0xbfb8aa3b, v181
	v_mul_f32_e32 v182, 0xbfb8aa3b, v182
	v_mul_f32_e32 v183, 0xbfb8aa3b, v183
	v_exp_f32_e32 v176, v176
	v_exp_f32_e32 v177, v177
	v_exp_f32_e32 v178, v178
	v_exp_f32_e32 v179, v179
	v_exp_f32_e32 v180, v180
	v_exp_f32_e32 v181, v181
	v_exp_f32_e32 v182, v182
	v_exp_f32_e32 v183, v183
	v_add_f32_e32 v176, 1.0, v176
	v_add_f32_e32 v177, 1.0, v177
	v_add_f32_e32 v178, 1.0, v178
	v_add_f32_e32 v179, 1.0, v179
	v_add_f32_e32 v180, 1.0, v180
	v_add_f32_e32 v181, 1.0, v181
	v_add_f32_e32 v182, 1.0, v182
	v_add_f32_e32 v183, 1.0, v183
	v_rcp_f32_e32 v176, v176
	v_rcp_f32_e32 v177, v177
	v_rcp_f32_e32 v178, v178
	v_rcp_f32_e32 v179, v179
	v_rcp_f32_e32 v180, v180
	v_rcp_f32_e32 v181, v181
	v_rcp_f32_e32 v182, v182
	v_rcp_f32_e32 v183, v183
	v_max_f32_e32 v176, 0x358637bd, v176
	v_max_f32_e32 v177, 0x358637bd, v177
	v_max_f32_e32 v178, 0x358637bd, v178
	v_max_f32_e32 v179, 0x358637bd, v179
	v_max_f32_e32 v180, 0x358637bd, v180
	v_max_f32_e32 v181, 0x358637bd, v181
	v_max_f32_e32 v182, 0x358637bd, v182
	v_max_f32_e32 v183, 0x358637bd, v183
	v_cvt_pk_bf16_f32 v184, v176, v177
	v_cvt_pk_bf16_f32 v185, v178, v179
	v_cvt_pk_bf16_f32 v186, v180, v181
	v_cvt_pk_bf16_f32 v187, v182, v183
	global_store_short v192, v184, s[62:63]
	global_store_short v192, v186, s[62:63] offset:64
	v_add_u32_e32 v192, 0x800, v192
	global_store_short_d16_hi v192, v184, s[62:63]
	global_store_short_d16_hi v192, v186, s[62:63] offset:64
	v_add_u32_e32 v192, 0x800, v192
	global_store_short v192, v185, s[62:63]
	global_store_short v192, v187, s[62:63] offset:64
	v_add_u32_e32 v192, 0x800, v192
	global_store_short_d16_hi v192, v185, s[62:63]
	global_store_short_d16_hi v192, v187, s[62:63] offset:64
	v_add_u32_e32 v192, 0x2800, v192
	s_waitcnt lgkmcnt(0)
	v_mul_f32_e32 v176, v44, v172
	v_mul_f32_e32 v177, v45, v173
	v_mul_f32_e32 v178, v46, v174
	v_mul_f32_e32 v179, v47, v175
	v_mul_f32_e32 v180, v28, v172
	v_mul_f32_e32 v181, v29, v173
	v_mul_f32_e32 v182, v30, v174
	v_mul_f32_e32 v183, v31, v175
	v_mul_f32_e32 v176, 0xbfb8aa3b, v176
	v_mul_f32_e32 v177, 0xbfb8aa3b, v177
	v_mul_f32_e32 v178, 0xbfb8aa3b, v178
	v_mul_f32_e32 v179, 0xbfb8aa3b, v179
	v_mul_f32_e32 v180, 0xbfb8aa3b, v180
	v_mul_f32_e32 v181, 0xbfb8aa3b, v181
	v_mul_f32_e32 v182, 0xbfb8aa3b, v182
	v_mul_f32_e32 v183, 0xbfb8aa3b, v183
	v_exp_f32_e32 v176, v176
	v_exp_f32_e32 v177, v177
	v_exp_f32_e32 v178, v178
	v_exp_f32_e32 v179, v179
	v_exp_f32_e32 v180, v180
	v_exp_f32_e32 v181, v181
	v_exp_f32_e32 v182, v182
	v_exp_f32_e32 v183, v183
	v_add_f32_e32 v176, 1.0, v176
	v_add_f32_e32 v177, 1.0, v177
	v_add_f32_e32 v178, 1.0, v178
	v_add_f32_e32 v179, 1.0, v179
	v_add_f32_e32 v180, 1.0, v180
	v_add_f32_e32 v181, 1.0, v181
	v_add_f32_e32 v182, 1.0, v182
	v_add_f32_e32 v183, 1.0, v183
	v_rcp_f32_e32 v176, v176
	v_rcp_f32_e32 v177, v177
	v_rcp_f32_e32 v178, v178
	v_rcp_f32_e32 v179, v179
	v_rcp_f32_e32 v180, v180
	v_rcp_f32_e32 v181, v181
	v_rcp_f32_e32 v182, v182
	v_rcp_f32_e32 v183, v183
	v_max_f32_e32 v176, 0x358637bd, v176
	v_max_f32_e32 v177, 0x358637bd, v177
	v_max_f32_e32 v178, 0x358637bd, v178
	v_max_f32_e32 v179, 0x358637bd, v179
	v_max_f32_e32 v180, 0x358637bd, v180
	v_max_f32_e32 v181, 0x358637bd, v181
	v_max_f32_e32 v182, 0x358637bd, v182
	v_max_f32_e32 v183, 0x358637bd, v183
	v_cvt_pk_bf16_f32 v188, v176, v177
	v_cvt_pk_bf16_f32 v189, v178, v179
	v_cvt_pk_bf16_f32 v190, v180, v181
	v_cvt_pk_bf16_f32 v191, v182, v183
	global_store_short v192, v188, s[62:63]
	global_store_short v192, v190, s[62:63] offset:64
	v_add_u32_e32 v192, 0x800, v192
	global_store_short_d16_hi v192, v188, s[62:63]
	global_store_short_d16_hi v192, v190, s[62:63] offset:64
	v_add_u32_e32 v192, 0x800, v192
	global_store_short v192, v189, s[62:63]
	global_store_short v192, v191, s[62:63] offset:64
	v_add_u32_e32 v192, 0x800, v192
	global_store_short_d16_hi v192, v189, s[62:63]
	global_store_short_d16_hi v192, v191, s[62:63] offset:64

.LBB0_3355:
	s_lshl_b64 s[22:23], s[10:11], 10
	s_waitcnt vmcnt(0)
	s_cmpk_lt_i32 s8, 0x4000
	s_cbranch_scc1 .Lp6x_e1_f
	v_readfirstlane_b32 s64, v208
	s_bitcmp1_b32 s64, 8
	s_cbranch_scc1 .Lp6x_e1_e
.Lp6x_e1_f:
	v_lshrrev_b32_e32 v197, 3, v208
	v_and_b32_e32 v197, 4, v197
	v_lshrrev_b32_e32 v195, 1, v208
	v_and_b32_e32 v195, 0x80, v195
	v_or_b32_e32 v195, v195, v197
	v_lshl_add_u32 v194, v195, 2, s33
	ds_read_b128 v[144:147], v194
	ds_read_b128 v[148:151], v194 offset:32
	ds_read_b128 v[152:155], v194 offset:64
	ds_read_b128 v[156:159], v194 offset:96
	ds_read_b128 v[160:163], v194 offset:128
	ds_read_b128 v[164:167], v194 offset:160
	ds_read_b128 v[168:171], v194 offset:192
	ds_read_b128 v[172:175], v194 offset:224
	v_and_b32_e32 v196, 0xdf, v208
	v_or_b32_e32 v196, s10, v196
	v_add_u32_e32 v197, s8, v195
	v_lshlrev_b32_e32 v197, 11, v197
	v_lshl_add_u32 v192, v196, 1, v197
	s_waitcnt lgkmcnt(7)
	v_mul_f32_e32 v176, v114, v144
	v_mul_f32_e32 v177, v115, v145
	v_mul_f32_e32 v178, v116, v146
	v_mul_f32_e32 v179, v117, v147
	v_mul_f32_e32 v180, v98, v144
	v_mul_f32_e32 v181, v99, v145
	v_mul_f32_e32 v182, v100, v146
	v_mul_f32_e32 v183, v101, v147
	ds_read_b128 v[144:147], v194 offset:256
	v_mul_f32_e32 v176, 0xbfb8aa3b, v176
	v_mul_f32_e32 v177, 0xbfb8aa3b, v177
	v_mul_f32_e32 v178, 0xbfb8aa3b, v178
	v_mul_f32_e32 v179, 0xbfb8aa3b, v179
	v_mul_f32_e32 v180, 0xbfb8aa3b, v180
	v_mul_f32_e32 v181, 0xbfb8aa3b, v181
	v_mul_f32_e32 v182, 0xbfb8aa3b, v182
	v_mul_f32_e32 v183, 0xbfb8aa3b, v183
	v_exp_f32_e32 v176, v176
	v_exp_f32_e32 v177, v177
	v_exp_f32_e32 v178, v178
	v_exp_f32_e32 v179, v179
	v_exp_f32_e32 v180, v180
	v_exp_f32_e32 v181, v181
	v_exp_f32_e32 v182, v182
	v_exp_f32_e32 v183, v183
	v_add_f32_e32 v176, 1.0, v176
	v_add_f32_e32 v177, 1.0, v177
	v_add_f32_e32 v178, 1.0, v178
	v_add_f32_e32 v179, 1.0, v179
	v_add_f32_e32 v180, 1.0, v180
	v_add_f32_e32 v181, 1.0, v181
	v_add_f32_e32 v182, 1.0, v182
	v_add_f32_e32 v183, 1.0, v183
	v_rcp_f32_e32 v176, v176
	v_rcp_f32_e32 v177, v177
	v_rcp_f32_e32 v178, v178
	v_rcp_f32_e32 v179, v179
	v_rcp_f32_e32 v180, v180
	v_rcp_f32_e32 v181, v181
	v_rcp_f32_e32 v182, v182
	v_rcp_f32_e32 v183, v183
	v_cvt_pk_bf16_f32 v184, v176, v177
	v_cvt_pk_bf16_f32 v185, v178, v179
	v_cvt_pk_bf16_f32 v186, v180, v181
	v_cvt_pk_bf16_f32 v187, v182, v183
	global_store_short v192, v184, s[18:19]
	global_store_short v192, v186, s[18:19] offset:64
	v_add_u32_e32 v192, 0x800, v192
	global_store_short_d16_hi v192, v184, s[18:19]
	global_store_short_d16_hi v192, v186, s[18:19] offset:64
	v_add_u32_e32 v192, 0x800, v192
	global_store_short v192, v185, s[18:19]
	global_store_short v192, v187, s[18:19] offset:64
	v_add_u32_e32 v192, 0x800, v192
	global_store_short_d16_hi v192, v185, s[18:19]
	global_store_short_d16_hi v192, v187, s[18:19] offset:64
	v_add_u32_e32 v192, 0x2800, v192
	s_waitcnt lgkmcnt(7)
	v_mul_f32_e32 v176, v118, v148
	v_mul_f32_e32 v177, v119, v149
	v_mul_f32_e32 v178, v120, v150
	v_mul_f32_e32 v179, v121, v151
	v_mul_f32_e32 v180, v102, v148
	v_mul_f32_e32 v181, v103, v149
	v_mul_f32_e32 v182, v104, v150
	v_mul_f32_e32 v183, v105, v151
	ds_read_b128 v[148:151], v194 offset:288
	v_mul_f32_e32 v176, 0xbfb8aa3b, v176
	v_mul_f32_e32 v177, 0xbfb8aa3b, v177
	v_mul_f32_e32 v178, 0xbfb8aa3b, v178
	v_mul_f32_e32 v179, 0xbfb8aa3b, v179
	v_mul_f32_e32 v180, 0xbfb8aa3b, v180
	v_mul_f32_e32 v181, 0xbfb8aa3b, v181
	v_mul_f32_e32 v182, 0xbfb8aa3b, v182
	v_mul_f32_e32 v183, 0xbfb8aa3b, v183
	v_exp_f32_e32 v176, v176
	v_exp_f32_e32 v177, v177
	v_exp_f32_e32 v178, v178
	v_exp_f32_e32 v179, v179
	v_exp_f32_e32 v180, v180
	v_exp_f32_e32 v181, v181
	v_exp_f32_e32 v182, v182
	v_exp_f32_e32 v183, v183
	v_add_f32_e32 v176, 1.0, v176
	v_add_f32_e32 v177, 1.0, v177
	v_add_f32_e32 v178, 1.0, v178
	v_add_f32_e32 v179, 1.0, v179
	v_add_f32_e32 v180, 1.0, v180
	v_add_f32_e32 v181, 1.0, v181
	v_add_f32_e32 v182, 1.0, v182
	v_add_f32_e32 v183, 1.0, v183
	v_rcp_f32_e32 v176, v176
	v_rcp_f32_e32 v177, v177
	v_rcp_f32_e32 v178, v178
	v_rcp_f32_e32 v179, v179
	v_rcp_f32_e32 v180, v180
	v_rcp_f32_e32 v181, v181
	v_rcp_f32_e32 v182, v182
	v_rcp_f32_e32 v183, v183
	v_cvt_pk_bf16_f32 v188, v176, v177
	v_cvt_pk_bf16_f32 v189, v178, v179
	v_cvt_pk_bf16_f32 v190, v180, v181
	v_cvt_pk_bf16_f32 v191, v182, v183
	global_store_short v192, v188, s[18:19]
	global_store_short v192, v190, s[18:19] offset:64
	v_add_u32_e32 v192, 0x800, v192
	global_store_short_d16_hi v192, v188, s[18:19]
	global_store_short_d16_hi v192, v190, s[18:19] offset:64
	v_add_u32_e32 v192, 0x800, v192
	global_store_short v192, v189, s[18:19]
	global_store_short v192, v191, s[18:19] offset:64
	v_add_u32_e32 v192, 0x800, v192
	global_store_short_d16_hi v192, v189, s[18:19]
	global_store_short_d16_hi v192, v191, s[18:19] offset:64
	v_add_u32_e32 v192, 0x2800, v192
	s_waitcnt lgkmcnt(7)
	v_mul_f32_e32 v176, v122, v152
	v_mul_f32_e32 v177, v123, v153
	v_mul_f32_e32 v178, v124, v154
	v_mul_f32_e32 v179, v125, v155
	v_mul_f32_e32 v180, v106, v152
	v_mul_f32_e32 v181, v107, v153
	v_mul_f32_e32 v182, v108, v154
	v_mul_f32_e32 v183, v109, v155
	ds_read_b128 v[152:155], v194 offset:320
	v_mul_f32_e32 v176, 0xbfb8aa3b, v176
	v_mul_f32_e32 v177, 0xbfb8aa3b, v177
	v_mul_f32_e32 v178, 0xbfb8aa3b, v178
	v_mul_f32_e32 v179, 0xbfb8aa3b, v179
	v_mul_f32_e32 v180, 0xbfb8aa3b, v180
	v_mul_f32_e32 v181, 0xbfb8aa3b, v181
	v_mul_f32_e32 v182, 0xbfb8aa3b, v182
	v_mul_f32_e32 v183, 0xbfb8aa3b, v183
	v_exp_f32_e32 v176, v176
	v_exp_f32_e32 v177, v177
	v_exp_f32_e32 v178, v178
	v_exp_f32_e32 v179, v179
	v_exp_f32_e32 v180, v180
	v_exp_f32_e32 v181, v181
	v_exp_f32_e32 v182, v182
	v_exp_f32_e32 v183, v183
	v_add_f32_e32 v176, 1.0, v176
	v_add_f32_e32 v177, 1.0, v177
	v_add_f32_e32 v178, 1.0, v178
	v_add_f32_e32 v179, 1.0, v179
	v_add_f32_e32 v180, 1.0, v180
	v_add_f32_e32 v181, 1.0, v181
	v_add_f32_e32 v182, 1.0, v182
	v_add_f32_e32 v183, 1.0, v183
	v_rcp_f32_e32 v176, v176
	v_rcp_f32_e32 v177, v177
	v_rcp_f32_e32 v178, v178
	v_rcp_f32_e32 v179, v179
	v_rcp_f32_e32 v180, v180
	v_rcp_f32_e32 v181, v181
	v_rcp_f32_e32 v182, v182
	v_rcp_f32_e32 v183, v183
	v_cvt_pk_bf16_f32 v184, v176, v177
	v_cvt_pk_bf16_f32 v185, v178, v179
	v_cvt_pk_bf16_f32 v186, v180, v181
	v_cvt_pk_bf16_f32 v187, v182, v183
	global_store_short v192, v184, s[18:19]
	global_store_short v192, v186, s[18:19] offset:64
	v_add_u32_e32 v192, 0x800, v192
	global_store_short_d16_hi v192, v184, s[18:19]
	global_store_short_d16_hi v192, v186, s[18:19] offset:64
	v_add_u32_e32 v192, 0x800, v192
	global_store_short v192, v185, s[18:19]
	global_store_short v192, v187, s[18:19] offset:64
	v_add_u32_e32 v192, 0x800, v192
	global_store_short_d16_hi v192, v185, s[18:19]
	global_store_short_d16_hi v192, v187, s[18:19] offset:64
	v_add_u32_e32 v192, 0x2800, v192
	s_waitcnt lgkmcnt(7)
	v_mul_f32_e32 v176, v126, v156
	v_mul_f32_e32 v177, v127, v157
	v_mul_f32_e32 v178, v128, v158
	v_mul_f32_e32 v179, v129, v159
	v_mul_f32_e32 v180, v110, v156
	v_mul_f32_e32 v181, v111, v157
	v_mul_f32_e32 v182, v112, v158
	v_mul_f32_e32 v183, v113, v159
	ds_read_b128 v[156:159], v194 offset:352
	v_mul_f32_e32 v176, 0xbfb8aa3b, v176
	v_mul_f32_e32 v177, 0xbfb8aa3b, v177
	v_mul_f32_e32 v178, 0xbfb8aa3b, v178
	v_mul_f32_e32 v179, 0xbfb8aa3b, v179
	v_mul_f32_e32 v180, 0xbfb8aa3b, v180
	v_mul_f32_e32 v181, 0xbfb8aa3b, v181
	v_mul_f32_e32 v182, 0xbfb8aa3b, v182
	v_mul_f32_e32 v183, 0xbfb8aa3b, v183
	v_exp_f32_e32 v176, v176
	v_exp_f32_e32 v177, v177
	v_exp_f32_e32 v178, v178
	v_exp_f32_e32 v179, v179
	v_exp_f32_e32 v180, v180
	v_exp_f32_e32 v181, v181
	v_exp_f32_e32 v182, v182
	v_exp_f32_e32 v183, v183
	v_add_f32_e32 v176, 1.0, v176
	v_add_f32_e32 v177, 1.0, v177
	v_add_f32_e32 v178, 1.0, v178
	v_add_f32_e32 v179, 1.0, v179
	v_add_f32_e32 v180, 1.0, v180
	v_add_f32_e32 v181, 1.0, v181
	v_add_f32_e32 v182, 1.0, v182
	v_add_f32_e32 v183, 1.0, v183
	v_rcp_f32_e32 v176, v176
	v_rcp_f32_e32 v177, v177
	v_rcp_f32_e32 v178, v178
	v_rcp_f32_e32 v179, v179
	v_rcp_f32_e32 v180, v180
	v_rcp_f32_e32 v181, v181
	v_rcp_f32_e32 v182, v182
	v_rcp_f32_e32 v183, v183
	v_cvt_pk_bf16_f32 v188, v176, v177
	v_cvt_pk_bf16_f32 v189, v178, v179
	v_cvt_pk_bf16_f32 v190, v180, v181
	v_cvt_pk_bf16_f32 v191, v182, v183
	global_store_short v192, v188, s[18:19]
	global_store_short v192, v190, s[18:19] offset:64
	v_add_u32_e32 v192, 0x800, v192
	global_store_short_d16_hi v192, v188, s[18:19]
	global_store_short_d16_hi v192, v190, s[18:19] offset:64
	v_add_u32_e32 v192, 0x800, v192
	global_store_short v192, v189, s[18:19]
	global_store_short v192, v191, s[18:19] offset:64
	v_add_u32_e32 v192, 0x800, v192
	global_store_short_d16_hi v192, v189, s[18:19]
	global_store_short_d16_hi v192, v191, s[18:19] offset:64
	v_add_u32_e32 v192, 0x2800, v192
	s_waitcnt lgkmcnt(7)
	v_mul_f32_e32 v176, v82, v160
	v_mul_f32_e32 v177, v83, v161
	v_mul_f32_e32 v178, v84, v162
	v_mul_f32_e32 v179, v85, v163
	v_mul_f32_e32 v180, v34, v160
	v_mul_f32_e32 v181, v35, v161
	v_mul_f32_e32 v182, v36, v162
	v_mul_f32_e32 v183, v37, v163
	ds_read_b128 v[160:163], v194 offset:384
	v_mul_f32_e32 v176, 0xbfb8aa3b, v176
	v_mul_f32_e32 v177, 0xbfb8aa3b, v177
	v_mul_f32_e32 v178, 0xbfb8aa3b, v178
	v_mul_f32_e32 v179, 0xbfb8aa3b, v179
	v_mul_f32_e32 v180, 0xbfb8aa3b, v180
	v_mul_f32_e32 v181, 0xbfb8aa3b, v181
	v_mul_f32_e32 v182, 0xbfb8aa3b, v182
	v_mul_f32_e32 v183, 0xbfb8aa3b, v183
	v_exp_f32_e32 v176, v176
	v_exp_f32_e32 v177, v177
	v_exp_f32_e32 v178, v178
	v_exp_f32_e32 v179, v179
	v_exp_f32_e32 v180, v180
	v_exp_f32_e32 v181, v181
	v_exp_f32_e32 v182, v182
	v_exp_f32_e32 v183, v183
	v_add_f32_e32 v176, 1.0, v176
	v_add_f32_e32 v177, 1.0, v177
	v_add_f32_e32 v178, 1.0, v178
	v_add_f32_e32 v179, 1.0, v179
	v_add_f32_e32 v180, 1.0, v180
	v_add_f32_e32 v181, 1.0, v181
	v_add_f32_e32 v182, 1.0, v182
	v_add_f32_e32 v183, 1.0, v183
	v_rcp_f32_e32 v176, v176
	v_rcp_f32_e32 v177, v177
	v_rcp_f32_e32 v178, v178
	v_rcp_f32_e32 v179, v179
	v_rcp_f32_e32 v180, v180
	v_rcp_f32_e32 v181, v181
	v_rcp_f32_e32 v182, v182
	v_rcp_f32_e32 v183, v183
	v_cvt_pk_bf16_f32 v184, v176, v177
	v_cvt_pk_bf16_f32 v185, v178, v179
	v_cvt_pk_bf16_f32 v186, v180, v181
	v_cvt_pk_bf16_f32 v187, v182, v183
	global_store_short v192, v184, s[18:19]
	global_store_short v192, v186, s[18:19] offset:64
	v_add_u32_e32 v192, 0x800, v192
	global_store_short_d16_hi v192, v184, s[18:19]
	global_store_short_d16_hi v192, v186, s[18:19] offset:64
	v_add_u32_e32 v192, 0x800, v192
	global_store_short v192, v185, s[18:19]
	global_store_short v192, v187, s[18:19] offset:64
	v_add_u32_e32 v192, 0x800, v192
	global_store_short_d16_hi v192, v185, s[18:19]
	global_store_short_d16_hi v192, v187, s[18:19] offset:64
	v_add_u32_e32 v192, 0x2800, v192
	s_waitcnt lgkmcnt(7)
	v_mul_f32_e32 v176, v86, v164
	v_mul_f32_e32 v177, v87, v165
	v_mul_f32_e32 v178, v88, v166
	v_mul_f32_e32 v179, v89, v167
	v_mul_f32_e32 v180, v38, v164
	v_mul_f32_e32 v181, v39, v165
	v_mul_f32_e32 v182, v40, v166
	v_mul_f32_e32 v183, v41, v167
	ds_read_b128 v[164:167], v194 offset:416
	v_mul_f32_e32 v176, 0xbfb8aa3b, v176
	v_mul_f32_e32 v177, 0xbfb8aa3b, v177
	v_mul_f32_e32 v178, 0xbfb8aa3b, v178
	v_mul_f32_e32 v179, 0xbfb8aa3b, v179
	v_mul_f32_e32 v180, 0xbfb8aa3b, v180
	v_mul_f32_e32 v181, 0xbfb8aa3b, v181
	v_mul_f32_e32 v182, 0xbfb8aa3b, v182
	v_mul_f32_e32 v183, 0xbfb8aa3b, v183
	v_exp_f32_e32 v176, v176
	v_exp_f32_e32 v177, v177
	v_exp_f32_e32 v178, v178
	v_exp_f32_e32 v179, v179
	v_exp_f32_e32 v180, v180
	v_exp_f32_e32 v181, v181
	v_exp_f32_e32 v182, v182
	v_exp_f32_e32 v183, v183
	v_add_f32_e32 v176, 1.0, v176
	v_add_f32_e32 v177, 1.0, v177
	v_add_f32_e32 v178, 1.0, v178
	v_add_f32_e32 v179, 1.0, v179
	v_add_f32_e32 v180, 1.0, v180
	v_add_f32_e32 v181, 1.0, v181
	v_add_f32_e32 v182, 1.0, v182
	v_add_f32_e32 v183, 1.0, v183
	v_rcp_f32_e32 v176, v176
	v_rcp_f32_e32 v177, v177
	v_rcp_f32_e32 v178, v178
	v_rcp_f32_e32 v179, v179
	v_rcp_f32_e32 v180, v180
	v_rcp_f32_e32 v181, v181
	v_rcp_f32_e32 v182, v182
	v_rcp_f32_e32 v183, v183
	v_cvt_pk_bf16_f32 v188, v176, v177
	v_cvt_pk_bf16_f32 v189, v178, v179
	v_cvt_pk_bf16_f32 v190, v180, v181
	v_cvt_pk_bf16_f32 v191, v182, v183
	global_store_short v192, v188, s[18:19]
	global_store_short v192, v190, s[18:19] offset:64
	v_add_u32_e32 v192, 0x800, v192
	global_store_short_d16_hi v192, v188, s[18:19]
	global_store_short_d16_hi v192, v190, s[18:19] offset:64
	v_add_u32_e32 v192, 0x800, v192
	global_store_short v192, v189, s[18:19]
	global_store_short v192, v191, s[18:19] offset:64
	v_add_u32_e32 v192, 0x800, v192
	global_store_short_d16_hi v192, v189, s[18:19]
	global_store_short_d16_hi v192, v191, s[18:19] offset:64
	v_add_u32_e32 v192, 0x2800, v192
	s_waitcnt lgkmcnt(7)
	v_mul_f32_e32 v176, v90, v168
	v_mul_f32_e32 v177, v91, v169
	v_mul_f32_e32 v178, v92, v170
	v_mul_f32_e32 v179, v93, v171
	v_mul_f32_e32 v180, v42, v168
	v_mul_f32_e32 v181, v43, v169
	v_mul_f32_e32 v182, v44, v170
	v_mul_f32_e32 v183, v45, v171
	ds_read_b128 v[168:171], v194 offset:448
	v_mul_f32_e32 v176, 0xbfb8aa3b, v176
	v_mul_f32_e32 v177, 0xbfb8aa3b, v177
	v_mul_f32_e32 v178, 0xbfb8aa3b, v178
	v_mul_f32_e32 v179, 0xbfb8aa3b, v179
	v_mul_f32_e32 v180, 0xbfb8aa3b, v180
	v_mul_f32_e32 v181, 0xbfb8aa3b, v181
	v_mul_f32_e32 v182, 0xbfb8aa3b, v182
	v_mul_f32_e32 v183, 0xbfb8aa3b, v183
	v_exp_f32_e32 v176, v176
	v_exp_f32_e32 v177, v177
	v_exp_f32_e32 v178, v178
	v_exp_f32_e32 v179, v179
	v_exp_f32_e32 v180, v180
	v_exp_f32_e32 v181, v181
	v_exp_f32_e32 v182, v182
	v_exp_f32_e32 v183, v183
	v_add_f32_e32 v176, 1.0, v176
	v_add_f32_e32 v177, 1.0, v177
	v_add_f32_e32 v178, 1.0, v178
	v_add_f32_e32 v179, 1.0, v179
	v_add_f32_e32 v180, 1.0, v180
	v_add_f32_e32 v181, 1.0, v181
	v_add_f32_e32 v182, 1.0, v182
	v_add_f32_e32 v183, 1.0, v183
	v_rcp_f32_e32 v176, v176
	v_rcp_f32_e32 v177, v177
	v_rcp_f32_e32 v178, v178
	v_rcp_f32_e32 v179, v179
	v_rcp_f32_e32 v180, v180
	v_rcp_f32_e32 v181, v181
	v_rcp_f32_e32 v182, v182
	v_rcp_f32_e32 v183, v183
	v_cvt_pk_bf16_f32 v184, v176, v177
	v_cvt_pk_bf16_f32 v185, v178, v179
	v_cvt_pk_bf16_f32 v186, v180, v181
	v_cvt_pk_bf16_f32 v187, v182, v183
	global_store_short v192, v184, s[18:19]
	global_store_short v192, v186, s[18:19] offset:64
	v_add_u32_e32 v192, 0x800, v192
	global_store_short_d16_hi v192, v184, s[18:19]
	global_store_short_d16_hi v192, v186, s[18:19] offset:64
	v_add_u32_e32 v192, 0x800, v192
	global_store_short v192, v185, s[18:19]
	global_store_short v192, v187, s[18:19] offset:64
	v_add_u32_e32 v192, 0x800, v192
	global_store_short_d16_hi v192, v185, s[18:19]
	global_store_short_d16_hi v192, v187, s[18:19] offset:64
	v_add_u32_e32 v192, 0x2800, v192
	s_waitcnt lgkmcnt(7)
	v_mul_f32_e32 v176, v94, v172
	v_mul_f32_e32 v177, v95, v173
	v_mul_f32_e32 v178, v96, v174
	v_mul_f32_e32 v179, v97, v175
	v_mul_f32_e32 v180, v46, v172
	v_mul_f32_e32 v181, v47, v173
	v_mul_f32_e32 v182, v48, v174
	v_mul_f32_e32 v183, v49, v175
	ds_read_b128 v[172:175], v194 offset:480
	v_mul_f32_e32 v176, 0xbfb8aa3b, v176
	v_mul_f32_e32 v177, 0xbfb8aa3b, v177
	v_mul_f32_e32 v178, 0xbfb8aa3b, v178
	v_mul_f32_e32 v179, 0xbfb8aa3b, v179
	v_mul_f32_e32 v180, 0xbfb8aa3b, v180
	v_mul_f32_e32 v181, 0xbfb8aa3b, v181
	v_mul_f32_e32 v182, 0xbfb8aa3b, v182
	v_mul_f32_e32 v183, 0xbfb8aa3b, v183
	v_exp_f32_e32 v176, v176
	v_exp_f32_e32 v177, v177
	v_exp_f32_e32 v178, v178
	v_exp_f32_e32 v179, v179
	v_exp_f32_e32 v180, v180
	v_exp_f32_e32 v181, v181
	v_exp_f32_e32 v182, v182
	v_exp_f32_e32 v183, v183
	v_add_f32_e32 v176, 1.0, v176
	v_add_f32_e32 v177, 1.0, v177
	v_add_f32_e32 v178, 1.0, v178
	v_add_f32_e32 v179, 1.0, v179
	v_add_f32_e32 v180, 1.0, v180
	v_add_f32_e32 v181, 1.0, v181
	v_add_f32_e32 v182, 1.0, v182
	v_add_f32_e32 v183, 1.0, v183
	v_rcp_f32_e32 v176, v176
	v_rcp_f32_e32 v177, v177
	v_rcp_f32_e32 v178, v178
	v_rcp_f32_e32 v179, v179
	v_rcp_f32_e32 v180, v180
	v_rcp_f32_e32 v181, v181
	v_rcp_f32_e32 v182, v182
	v_rcp_f32_e32 v183, v183
	v_cvt_pk_bf16_f32 v188, v176, v177
	v_cvt_pk_bf16_f32 v189, v178, v179
	v_cvt_pk_bf16_f32 v190, v180, v181
	v_cvt_pk_bf16_f32 v191, v182, v183
	global_store_short v192, v188, s[18:19]
	global_store_short v192, v190, s[18:19] offset:64
	v_add_u32_e32 v192, 0x800, v192
	global_store_short_d16_hi v192, v188, s[18:19]
	global_store_short_d16_hi v192, v190, s[18:19] offset:64
	v_add_u32_e32 v192, 0x800, v192
	global_store_short v192, v189, s[18:19]
	global_store_short v192, v191, s[18:19] offset:64
	v_add_u32_e32 v192, 0x800, v192
	global_store_short_d16_hi v192, v189, s[18:19]
	global_store_short_d16_hi v192, v191, s[18:19] offset:64
	v_add_u32_e32 v192, 0x2800, v192
	s_cmpk_lt_i32 s8, 0x4000
	s_cbranch_scc1 .Lp6x_e1_c
	s_waitcnt lgkmcnt(0)
	s_branch .Lp6x_e1_e
.Lp6x_e1_c:
	s_waitcnt lgkmcnt(7)
	v_mul_f32_e32 v176, v66, v144
	v_mul_f32_e32 v177, v67, v145
	v_mul_f32_e32 v178, v68, v146
	v_mul_f32_e32 v179, v69, v147
	v_mul_f32_e32 v180, v50, v144
	v_mul_f32_e32 v181, v51, v145
	v_mul_f32_e32 v182, v52, v146
	v_mul_f32_e32 v183, v53, v147
	v_mul_f32_e32 v176, 0xbfb8aa3b, v176
	v_mul_f32_e32 v177, 0xbfb8aa3b, v177
	v_mul_f32_e32 v178, 0xbfb8aa3b, v178
	v_mul_f32_e32 v179, 0xbfb8aa3b, v179
	v_mul_f32_e32 v180, 0xbfb8aa3b, v180
	v_mul_f32_e32 v181, 0xbfb8aa3b, v181
	v_mul_f32_e32 v182, 0xbfb8aa3b, v182
	v_mul_f32_e32 v183, 0xbfb8aa3b, v183
	v_exp_f32_e32 v176, v176
	v_exp_f32_e32 v177, v177
	v_exp_f32_e32 v178, v178
	v_exp_f32_e32 v179, v179
	v_exp_f32_e32 v180, v180
	v_exp_f32_e32 v181, v181
	v_exp_f32_e32 v182, v182
	v_exp_f32_e32 v183, v183
	v_add_f32_e32 v176, 1.0, v176
	v_add_f32_e32 v177, 1.0, v177
	v_add_f32_e32 v178, 1.0, v178
	v_add_f32_e32 v179, 1.0, v179
	v_add_f32_e32 v180, 1.0, v180
	v_add_f32_e32 v181, 1.0, v181
	v_add_f32_e32 v182, 1.0, v182
	v_add_f32_e32 v183, 1.0, v183
	v_rcp_f32_e32 v176, v176
	v_rcp_f32_e32 v177, v177
	v_rcp_f32_e32 v178, v178
	v_rcp_f32_e32 v179, v179
	v_rcp_f32_e32 v180, v180
	v_rcp_f32_e32 v181, v181
	v_rcp_f32_e32 v182, v182
	v_rcp_f32_e32 v183, v183
	v_cvt_pk_bf16_f32 v184, v176, v177
	v_cvt_pk_bf16_f32 v185, v178, v179
	v_cvt_pk_bf16_f32 v186, v180, v181
	v_cvt_pk_bf16_f32 v187, v182, v183
	global_store_short v192, v184, s[18:19]
	global_store_short v192, v186, s[18:19] offset:64
	v_add_u32_e32 v192, 0x800, v192
	global_store_short_d16_hi v192, v184, s[18:19]
	global_store_short_d16_hi v192, v186, s[18:19] offset:64
	v_add_u32_e32 v192, 0x800, v192
	global_store_short v192, v185, s[18:19]
	global_store_short v192, v187, s[18:19] offset:64
	v_add_u32_e32 v192, 0x800, v192
	global_store_short_d16_hi v192, v185, s[18:19]
	global_store_short_d16_hi v192, v187, s[18:19] offset:64
	v_add_u32_e32 v192, 0x2800, v192
	s_waitcnt lgkmcnt(6)
	v_mul_f32_e32 v176, v70, v148
	v_mul_f32_e32 v177, v71, v149
	v_mul_f32_e32 v178, v72, v150
	v_mul_f32_e32 v179, v73, v151
	v_mul_f32_e32 v180, v54, v148
	v_mul_f32_e32 v181, v55, v149
	v_mul_f32_e32 v182, v56, v150
	v_mul_f32_e32 v183, v57, v151
	v_mul_f32_e32 v176, 0xbfb8aa3b, v176
	v_mul_f32_e32 v177, 0xbfb8aa3b, v177
	v_mul_f32_e32 v178, 0xbfb8aa3b, v178
	v_mul_f32_e32 v179, 0xbfb8aa3b, v179
	v_mul_f32_e32 v180, 0xbfb8aa3b, v180
	v_mul_f32_e32 v181, 0xbfb8aa3b, v181
	v_mul_f32_e32 v182, 0xbfb8aa3b, v182
	v_mul_f32_e32 v183, 0xbfb8aa3b, v183
	v_exp_f32_e32 v176, v176
	v_exp_f32_e32 v177, v177
	v_exp_f32_e32 v178, v178
	v_exp_f32_e32 v179, v179
	v_exp_f32_e32 v180, v180
	v_exp_f32_e32 v181, v181
	v_exp_f32_e32 v182, v182
	v_exp_f32_e32 v183, v183
	v_add_f32_e32 v176, 1.0, v176
	v_add_f32_e32 v177, 1.0, v177
	v_add_f32_e32 v178, 1.0, v178
	v_add_f32_e32 v179, 1.0, v179
	v_add_f32_e32 v180, 1.0, v180
	v_add_f32_e32 v181, 1.0, v181
	v_add_f32_e32 v182, 1.0, v182
	v_add_f32_e32 v183, 1.0, v183
	v_rcp_f32_e32 v176, v176
	v_rcp_f32_e32 v177, v177
	v_rcp_f32_e32 v178, v178
	v_rcp_f32_e32 v179, v179
	v_rcp_f32_e32 v180, v180
	v_rcp_f32_e32 v181, v181
	v_rcp_f32_e32 v182, v182
	v_rcp_f32_e32 v183, v183
	v_cvt_pk_bf16_f32 v188, v176, v177
	v_cvt_pk_bf16_f32 v189, v178, v179
	v_cvt_pk_bf16_f32 v190, v180, v181
	v_cvt_pk_bf16_f32 v191, v182, v183
	global_store_short v192, v188, s[18:19]
	global_store_short v192, v190, s[18:19] offset:64
	v_add_u32_e32 v192, 0x800, v192
	global_store_short_d16_hi v192, v188, s[18:19]
	global_store_short_d16_hi v192, v190, s[18:19] offset:64
	v_add_u32_e32 v192, 0x800, v192
	global_store_short v192, v189, s[18:19]
	global_store_short v192, v191, s[18:19] offset:64
	v_add_u32_e32 v192, 0x800, v192
	global_store_short_d16_hi v192, v189, s[18:19]
	global_store_short_d16_hi v192, v191, s[18:19] offset:64
	v_add_u32_e32 v192, 0x2800, v192
	s_waitcnt lgkmcnt(5)
	v_mul_f32_e32 v176, v74, v152
	v_mul_f32_e32 v177, v75, v153
	v_mul_f32_e32 v178, v76, v154
	v_mul_f32_e32 v179, v77, v155
	v_mul_f32_e32 v180, v58, v152
	v_mul_f32_e32 v181, v59, v153
	v_mul_f32_e32 v182, v60, v154
	v_mul_f32_e32 v183, v61, v155
	v_mul_f32_e32 v176, 0xbfb8aa3b, v176
	v_mul_f32_e32 v177, 0xbfb8aa3b, v177
	v_mul_f32_e32 v178, 0xbfb8aa3b, v178
	v_mul_f32_e32 v179, 0xbfb8aa3b, v179
	v_mul_f32_e32 v180, 0xbfb8aa3b, v180
	v_mul_f32_e32 v181, 0xbfb8aa3b, v181
	v_mul_f32_e32 v182, 0xbfb8aa3b, v182
	v_mul_f32_e32 v183, 0xbfb8aa3b, v183
	v_exp_f32_e32 v176, v176
	v_exp_f32_e32 v177, v177
	v_exp_f32_e32 v178, v178
	v_exp_f32_e32 v179, v179
	v_exp_f32_e32 v180, v180
	v_exp_f32_e32 v181, v181
	v_exp_f32_e32 v182, v182
	v_exp_f32_e32 v183, v183
	v_add_f32_e32 v176, 1.0, v176
	v_add_f32_e32 v177, 1.0, v177
	v_add_f32_e32 v178, 1.0, v178
	v_add_f32_e32 v179, 1.0, v179
	v_add_f32_e32 v180, 1.0, v180
	v_add_f32_e32 v181, 1.0, v181
	v_add_f32_e32 v182, 1.0, v182
	v_add_f32_e32 v183, 1.0, v183
	v_rcp_f32_e32 v176, v176
	v_rcp_f32_e32 v177, v177
	v_rcp_f32_e32 v178, v178
	v_rcp_f32_e32 v179, v179
	v_rcp_f32_e32 v180, v180
	v_rcp_f32_e32 v181, v181
	v_rcp_f32_e32 v182, v182
	v_rcp_f32_e32 v183, v183
	v_cvt_pk_bf16_f32 v184, v176, v177
	v_cvt_pk_bf16_f32 v185, v178, v179
	v_cvt_pk_bf16_f32 v186, v180, v181
	v_cvt_pk_bf16_f32 v187, v182, v183
	global_store_short v192, v184, s[18:19]
	global_store_short v192, v186, s[18:19] offset:64
	v_add_u32_e32 v192, 0x800, v192
	global_store_short_d16_hi v192, v184, s[18:19]
	global_store_short_d16_hi v192, v186, s[18:19] offset:64
	v_add_u32_e32 v192, 0x800, v192
	global_store_short v192, v185, s[18:19]
	global_store_short v192, v187, s[18:19] offset:64
	v_add_u32_e32 v192, 0x800, v192
	global_store_short_d16_hi v192, v185, s[18:19]
	global_store_short_d16_hi v192, v187, s[18:19] offset:64
	v_add_u32_e32 v192, 0x2800, v192
	s_waitcnt lgkmcnt(4)
	v_mul_f32_e32 v176, v78, v156
	v_mul_f32_e32 v177, v79, v157
	v_mul_f32_e32 v178, v80, v158
	v_mul_f32_e32 v179, v81, v159
	v_mul_f32_e32 v180, v62, v156
	v_mul_f32_e32 v181, v63, v157
	v_mul_f32_e32 v182, v64, v158
	v_mul_f32_e32 v183, v65, v159
	v_mul_f32_e32 v176, 0xbfb8aa3b, v176
	v_mul_f32_e32 v177, 0xbfb8aa3b, v177
	v_mul_f32_e32 v178, 0xbfb8aa3b, v178
	v_mul_f32_e32 v179, 0xbfb8aa3b, v179
	v_mul_f32_e32 v180, 0xbfb8aa3b, v180
	v_mul_f32_e32 v181, 0xbfb8aa3b, v181
	v_mul_f32_e32 v182, 0xbfb8aa3b, v182
	v_mul_f32_e32 v183, 0xbfb8aa3b, v183
	v_exp_f32_e32 v176, v176
	v_exp_f32_e32 v177, v177
	v_exp_f32_e32 v178, v178
	v_exp_f32_e32 v179, v179
	v_exp_f32_e32 v180, v180
	v_exp_f32_e32 v181, v181
	v_exp_f32_e32 v182, v182
	v_exp_f32_e32 v183, v183
	v_add_f32_e32 v176, 1.0, v176
	v_add_f32_e32 v177, 1.0, v177
	v_add_f32_e32 v178, 1.0, v178
	v_add_f32_e32 v179, 1.0, v179
	v_add_f32_e32 v180, 1.0, v180
	v_add_f32_e32 v181, 1.0, v181
	v_add_f32_e32 v182, 1.0, v182
	v_add_f32_e32 v183, 1.0, v183
	v_rcp_f32_e32 v176, v176
	v_rcp_f32_e32 v177, v177
	v_rcp_f32_e32 v178, v178
	v_rcp_f32_e32 v179, v179
	v_rcp_f32_e32 v180, v180
	v_rcp_f32_e32 v181, v181
	v_rcp_f32_e32 v182, v182
	v_rcp_f32_e32 v183, v183
	v_cvt_pk_bf16_f32 v188, v176, v177
	v_cvt_pk_bf16_f32 v189, v178, v179
	v_cvt_pk_bf16_f32 v190, v180, v181
	v_cvt_pk_bf16_f32 v191, v182, v183
	global_store_short v192, v188, s[18:19]
	global_store_short v192, v190, s[18:19] offset:64
	v_add_u32_e32 v192, 0x800, v192
	global_store_short_d16_hi v192, v188, s[18:19]
	global_store_short_d16_hi v192, v190, s[18:19] offset:64
	v_add_u32_e32 v192, 0x800, v192
	global_store_short v192, v189, s[18:19]
	global_store_short v192, v191, s[18:19] offset:64
	v_add_u32_e32 v192, 0x800, v192
	global_store_short_d16_hi v192, v189, s[18:19]
	global_store_short_d16_hi v192, v191, s[18:19] offset:64
	v_add_u32_e32 v192, 0x2800, v192
	s_waitcnt lgkmcnt(3)
	v_mul_f32_e32 v176, v18, v160
	v_mul_f32_e32 v177, v19, v161
	v_mul_f32_e32 v178, v20, v162
	v_mul_f32_e32 v179, v21, v163
	v_mul_f32_e32 v180, v2, v160
	v_mul_f32_e32 v181, v3, v161
	v_mul_f32_e32 v182, v4, v162
	v_mul_f32_e32 v183, v5, v163
	v_mul_f32_e32 v176, 0xbfb8aa3b, v176
	v_mul_f32_e32 v177, 0xbfb8aa3b, v177
	v_mul_f32_e32 v178, 0xbfb8aa3b, v178
	v_mul_f32_e32 v179, 0xbfb8aa3b, v179
	v_mul_f32_e32 v180, 0xbfb8aa3b, v180
	v_mul_f32_e32 v181, 0xbfb8aa3b, v181
	v_mul_f32_e32 v182, 0xbfb8aa3b, v182
	v_mul_f32_e32 v183, 0xbfb8aa3b, v183
	v_exp_f32_e32 v176, v176
	v_exp_f32_e32 v177, v177
	v_exp_f32_e32 v178, v178
	v_exp_f32_e32 v179, v179
	v_exp_f32_e32 v180, v180
	v_exp_f32_e32 v181, v181
	v_exp_f32_e32 v182, v182
	v_exp_f32_e32 v183, v183
	v_add_f32_e32 v176, 1.0, v176
	v_add_f32_e32 v177, 1.0, v177
	v_add_f32_e32 v178, 1.0, v178
	v_add_f32_e32 v179, 1.0, v179
	v_add_f32_e32 v180, 1.0, v180
	v_add_f32_e32 v181, 1.0, v181
	v_add_f32_e32 v182, 1.0, v182
	v_add_f32_e32 v183, 1.0, v183
	v_rcp_f32_e32 v176, v176
	v_rcp_f32_e32 v177, v177
	v_rcp_f32_e32 v178, v178
	v_rcp_f32_e32 v179, v179
	v_rcp_f32_e32 v180, v180
	v_rcp_f32_e32 v181, v181
	v_rcp_f32_e32 v182, v182
	v_rcp_f32_e32 v183, v183
	v_cvt_pk_bf16_f32 v184, v176, v177
	v_cvt_pk_bf16_f32 v185, v178, v179
	v_cvt_pk_bf16_f32 v186, v180, v181
	v_cvt_pk_bf16_f32 v187, v182, v183
	global_store_short v192, v184, s[18:19]
	global_store_short v192, v186, s[18:19] offset:64
	v_add_u32_e32 v192, 0x800, v192
	global_store_short_d16_hi v192, v184, s[18:19]
	global_store_short_d16_hi v192, v186, s[18:19] offset:64
	v_add_u32_e32 v192, 0x800, v192
	global_store_short v192, v185, s[18:19]
	global_store_short v192, v187, s[18:19] offset:64
	v_add_u32_e32 v192, 0x800, v192
	global_store_short_d16_hi v192, v185, s[18:19]
	global_store_short_d16_hi v192, v187, s[18:19] offset:64
	v_add_u32_e32 v192, 0x2800, v192
	s_waitcnt lgkmcnt(2)
	v_mul_f32_e32 v176, v22, v164
	v_mul_f32_e32 v177, v23, v165
	v_mul_f32_e32 v178, v24, v166
	v_mul_f32_e32 v179, v25, v167
	v_mul_f32_e32 v180, v6, v164
	v_mul_f32_e32 v181, v7, v165
	v_mul_f32_e32 v182, v8, v166
	v_mul_f32_e32 v183, v9, v167
	v_mul_f32_e32 v176, 0xbfb8aa3b, v176
	v_mul_f32_e32 v177, 0xbfb8aa3b, v177
	v_mul_f32_e32 v178, 0xbfb8aa3b, v178
	v_mul_f32_e32 v179, 0xbfb8aa3b, v179
	v_mul_f32_e32 v180, 0xbfb8aa3b, v180
	v_mul_f32_e32 v181, 0xbfb8aa3b, v181
	v_mul_f32_e32 v182, 0xbfb8aa3b, v182
	v_mul_f32_e32 v183, 0xbfb8aa3b, v183
	v_exp_f32_e32 v176, v176
	v_exp_f32_e32 v177, v177
	v_exp_f32_e32 v178, v178
	v_exp_f32_e32 v179, v179
	v_exp_f32_e32 v180, v180
	v_exp_f32_e32 v181, v181
	v_exp_f32_e32 v182, v182
	v_exp_f32_e32 v183, v183
	v_add_f32_e32 v176, 1.0, v176
	v_add_f32_e32 v177, 1.0, v177
	v_add_f32_e32 v178, 1.0, v178
	v_add_f32_e32 v179, 1.0, v179
	v_add_f32_e32 v180, 1.0, v180
	v_add_f32_e32 v181, 1.0, v181
	v_add_f32_e32 v182, 1.0, v182
	v_add_f32_e32 v183, 1.0, v183
	v_rcp_f32_e32 v176, v176
	v_rcp_f32_e32 v177, v177
	v_rcp_f32_e32 v178, v178
	v_rcp_f32_e32 v179, v179
	v_rcp_f32_e32 v180, v180
	v_rcp_f32_e32 v181, v181
	v_rcp_f32_e32 v182, v182
	v_rcp_f32_e32 v183, v183
	v_cvt_pk_bf16_f32 v188, v176, v177
	v_cvt_pk_bf16_f32 v189, v178, v179
	v_cvt_pk_bf16_f32 v190, v180, v181
	v_cvt_pk_bf16_f32 v191, v182, v183
	global_store_short v192, v188, s[18:19]
	global_store_short v192, v190, s[18:19] offset:64
	v_add_u32_e32 v192, 0x800, v192
	global_store_short_d16_hi v192, v188, s[18:19]
	global_store_short_d16_hi v192, v190, s[18:19] offset:64
	v_add_u32_e32 v192, 0x800, v192
	global_store_short v192, v189, s[18:19]
	global_store_short v192, v191, s[18:19] offset:64
	v_add_u32_e32 v192, 0x800, v192
	global_store_short_d16_hi v192, v189, s[18:19]
	global_store_short_d16_hi v192, v191, s[18:19] offset:64
	v_add_u32_e32 v192, 0x2800, v192
	s_waitcnt lgkmcnt(1)
	v_mul_f32_e32 v176, v26, v168
	v_mul_f32_e32 v177, v27, v169
	v_mul_f32_e32 v178, v28, v170
	v_mul_f32_e32 v179, v29, v171
	v_mul_f32_e32 v180, v10, v168
	v_mul_f32_e32 v181, v11, v169
	v_mul_f32_e32 v182, v12, v170
	v_mul_f32_e32 v183, v13, v171
	v_mul_f32_e32 v176, 0xbfb8aa3b, v176
	v_mul_f32_e32 v177, 0xbfb8aa3b, v177
	v_mul_f32_e32 v178, 0xbfb8aa3b, v178
	v_mul_f32_e32 v179, 0xbfb8aa3b, v179
	v_mul_f32_e32 v180, 0xbfb8aa3b, v180
	v_mul_f32_e32 v181, 0xbfb8aa3b, v181
	v_mul_f32_e32 v182, 0xbfb8aa3b, v182
	v_mul_f32_e32 v183, 0xbfb8aa3b, v183
	v_exp_f32_e32 v176, v176
	v_exp_f32_e32 v177, v177
	v_exp_f32_e32 v178, v178
	v_exp_f32_e32 v179, v179
	v_exp_f32_e32 v180, v180
	v_exp_f32_e32 v181, v181
	v_exp_f32_e32 v182, v182
	v_exp_f32_e32 v183, v183
	v_add_f32_e32 v176, 1.0, v176
	v_add_f32_e32 v177, 1.0, v177
	v_add_f32_e32 v178, 1.0, v178
	v_add_f32_e32 v179, 1.0, v179
	v_add_f32_e32 v180, 1.0, v180
	v_add_f32_e32 v181, 1.0, v181
	v_add_f32_e32 v182, 1.0, v182
	v_add_f32_e32 v183, 1.0, v183
	v_rcp_f32_e32 v176, v176
	v_rcp_f32_e32 v177, v177
	v_rcp_f32_e32 v178, v178
	v_rcp_f32_e32 v179, v179
	v_rcp_f32_e32 v180, v180
	v_rcp_f32_e32 v181, v181
	v_rcp_f32_e32 v182, v182
	v_rcp_f32_e32 v183, v183
	v_cvt_pk_bf16_f32 v184, v176, v177
	v_cvt_pk_bf16_f32 v185, v178, v179
	v_cvt_pk_bf16_f32 v186, v180, v181
	v_cvt_pk_bf16_f32 v187, v182, v183
	global_store_short v192, v184, s[18:19]
	global_store_short v192, v186, s[18:19] offset:64
	v_add_u32_e32 v192, 0x800, v192
	global_store_short_d16_hi v192, v184, s[18:19]
	global_store_short_d16_hi v192, v186, s[18:19] offset:64
	v_add_u32_e32 v192, 0x800, v192
	global_store_short v192, v185, s[18:19]
	global_store_short v192, v187, s[18:19] offset:64
	v_add_u32_e32 v192, 0x800, v192
	global_store_short_d16_hi v192, v185, s[18:19]
	global_store_short_d16_hi v192, v187, s[18:19] offset:64
	v_add_u32_e32 v192, 0x2800, v192
	s_waitcnt lgkmcnt(0)
	v_mul_f32_e32 v176, v30, v172
	v_mul_f32_e32 v177, v31, v173
	v_mul_f32_e32 v178, v32, v174
	v_mul_f32_e32 v179, v33, v175
	v_mul_f32_e32 v180, v14, v172
	v_mul_f32_e32 v181, v15, v173
	v_mul_f32_e32 v182, v16, v174
	v_mul_f32_e32 v183, v17, v175
	v_mul_f32_e32 v176, 0xbfb8aa3b, v176
	v_mul_f32_e32 v177, 0xbfb8aa3b, v177
	v_mul_f32_e32 v178, 0xbfb8aa3b, v178
	v_mul_f32_e32 v179, 0xbfb8aa3b, v179
	v_mul_f32_e32 v180, 0xbfb8aa3b, v180
	v_mul_f32_e32 v181, 0xbfb8aa3b, v181
	v_mul_f32_e32 v182, 0xbfb8aa3b, v182
	v_mul_f32_e32 v183, 0xbfb8aa3b, v183
	v_exp_f32_e32 v176, v176
	v_exp_f32_e32 v177, v177
	v_exp_f32_e32 v178, v178
	v_exp_f32_e32 v179, v179
	v_exp_f32_e32 v180, v180
	v_exp_f32_e32 v181, v181
	v_exp_f32_e32 v182, v182
	v_exp_f32_e32 v183, v183
	v_add_f32_e32 v176, 1.0, v176
	v_add_f32_e32 v177, 1.0, v177
	v_add_f32_e32 v178, 1.0, v178
	v_add_f32_e32 v179, 1.0, v179
	v_add_f32_e32 v180, 1.0, v180
	v_add_f32_e32 v181, 1.0, v181
	v_add_f32_e32 v182, 1.0, v182
	v_add_f32_e32 v183, 1.0, v183
	v_rcp_f32_e32 v176, v176
	v_rcp_f32_e32 v177, v177
	v_rcp_f32_e32 v178, v178
	v_rcp_f32_e32 v179, v179
	v_rcp_f32_e32 v180, v180
	v_rcp_f32_e32 v181, v181
	v_rcp_f32_e32 v182, v182
	v_rcp_f32_e32 v183, v183
	v_cvt_pk_bf16_f32 v188, v176, v177
	v_cvt_pk_bf16_f32 v189, v178, v179
	v_cvt_pk_bf16_f32 v190, v180, v181
	v_cvt_pk_bf16_f32 v191, v182, v183
	global_store_short v192, v188, s[18:19]
	global_store_short v192, v190, s[18:19] offset:64
	v_add_u32_e32 v192, 0x800, v192
	global_store_short_d16_hi v192, v188, s[18:19]
	global_store_short_d16_hi v192, v190, s[18:19] offset:64
	v_add_u32_e32 v192, 0x800, v192
	global_store_short v192, v189, s[18:19]
	global_store_short v192, v191, s[18:19] offset:64
	v_add_u32_e32 v192, 0x800, v192
	global_store_short_d16_hi v192, v189, s[18:19]
	global_store_short_d16_hi v192, v191, s[18:19] offset:64
